# same as previous but without the XCD-local sync barriers in the gather (they no longer pay)
# speedup vs baseline: 1.0085x; 1.0085x over previous
; DEV void sort_lists(int lane, int& myi0, int& myi1, float& myg0, float& myg1) {
; #pragma unroll
;     for (int k = 2; k <= 128; k <<= 1) {
; #pragma unroll
;       for (int j = k >> 1; j >= 1; j >>= 1) {
;         if (j == 64) {
;           const bool sw_ = myi1 < myi0;
;           const int ti = sw_ ? myi1 : myi0, tj = sw_ ? myi0 : myi1; const float tg = sw_ ? myg1 : myg0, th = sw_ ? myg0 : myg1;
;           myi0 = ti; myi1 = tj; myg0 = tg; myg1 = th;
;         } else {
;           const bool lower = (lane & j) == 0;
;           {
;             const bool up = (k == 128) ? true : ((k == 64) ? true : ((lane & k) == 0));
;             const int oi = __shfl_xor(myi0, j); const float og = __shfl_xor(myg0, j);
;             const bool take = (lower == up) ? (oi < myi0) : (oi > myi0);
;             myi0 = take ? oi : myi0; myg0 = take ? og : myg0;
;           }
;           {
;             const bool up = (k == 128) ? true : ((k == 64) ? false : ((lane & k) == 0));
;             const int oi = __shfl_xor(myi1, j); const float og = __shfl_xor(myg1, j);
;             const bool take = (lower == up) ? (oi < myi1) : (oi > myi1);
;             myi1 = take ? oi : myi1; myg1 = take ? og : myg1;
;           }
;         }
;       }
;     }
; }
; DEV void peer_gather(const Params& P, int l, int m0, const int* idxs, const float* gs) {
;     ...
;   int ni0 = idxs[(wid * 16) * 128 + lane], ni1 = idxs[(wid * 16) * 128 + 64 + lane];
;   float ng0 = gs[(wid * 16) * 128 + lane], ng1 = gs[(wid * 16) * 128 + 64 + lane];
.Lpg0_p0:
	v_readlane_b32 s82, v231, 26
	v_readlane_b32 s83, v231, 27
	s_nop 4
	s_lshl_b32 s98, s2, 2
	s_add_u32 s98, s98, s33
	s_add_u32 s98, s98, 0
	s_lshl_b32 s98, s98, 9
	v_add_u32_e32 v116, s98, v234
	global_load_dword v241, v116, s[82:83]
	global_load_dword v242, v116, s[82:83] offset:256
	s_lshl_b32 s98, s2, 2
	s_add_u32 s98, s98, s33
	s_add_u32 s98, s98, 1
	s_lshl_b32 s98, s98, 9
	v_add_u32_e32 v117, s98, v234
	global_load_dword v243, v117, s[82:83]
	global_load_dword v244, v117, s[82:83] offset:256
	s_lshl_b32 s98, s2, 2
	s_add_u32 s98, s98, s33
	s_add_u32 s98, s98, 2
	s_lshl_b32 s98, s98, 9
	v_add_u32_e32 v118, s98, v234
	global_load_dword v245, v118, s[82:83]
	global_load_dword v246, v118, s[82:83] offset:256
	s_lshl_b32 s98, s2, 2
	s_add_u32 s98, s98, s33
	s_add_u32 s98, s98, 3
	s_lshl_b32 s98, s98, 9
	v_add_u32_e32 v119, s98, v234
	global_load_dword v247, v119, s[82:83]
	global_load_dword v248, v119, s[82:83] offset:256
	s_waitcnt vmcnt(0)
	v_or_b32_e32 v116, 64, v233
	v_lshl_or_b32 v241, v241, 7, v233
	v_lshl_or_b32 v242, v242, 7, v116
	v_lshl_or_b32 v243, v243, 7, v233
	v_lshl_or_b32 v244, v244, 7, v116
	v_lshl_or_b32 v245, v245, 7, v233
	v_lshl_or_b32 v246, v246, 7, v116
	v_lshl_or_b32 v247, v247, 7, v233
	v_lshl_or_b32 v248, v248, 7, v116
	v_xor_b32_e32 v116, 4, v234
	ds_bpermute_b32 v0, v116, v241
	ds_bpermute_b32 v1, v116, v243
	ds_bpermute_b32 v2, v116, v245
	ds_bpermute_b32 v3, v116, v247
	ds_bpermute_b32 v4, v116, v242
	ds_bpermute_b32 v5, v116, v244
	ds_bpermute_b32 v6, v116, v246
	ds_bpermute_b32 v7, v116, v248
	s_waitcnt lgkmcnt(0)
	s_mov_b32 s88, 0x99999999
	s_mov_b32 s89, 0x99999999
	v_min_u32_e32 v104, v241, v0
	v_max_u32_e32 v105, v241, v0
	v_cndmask_b32_e64 v241, v105, v104, s[88:89]
	v_min_u32_e32 v106, v243, v1
	v_max_u32_e32 v107, v243, v1
	v_cndmask_b32_e64 v243, v107, v106, s[88:89]
	v_min_u32_e32 v104, v245, v2
	v_max_u32_e32 v105, v245, v2
	v_cndmask_b32_e64 v245, v105, v104, s[88:89]
	v_min_u32_e32 v106, v247, v3
	v_max_u32_e32 v107, v247, v3
	v_cndmask_b32_e64 v247, v107, v106, s[88:89]
	v_min_u32_e32 v104, v242, v4
	v_max_u32_e32 v105, v242, v4
	v_cndmask_b32_e64 v242, v105, v104, s[88:89]
	v_min_u32_e32 v106, v244, v5
	v_max_u32_e32 v107, v244, v5
	v_cndmask_b32_e64 v244, v107, v106, s[88:89]
	v_min_u32_e32 v104, v246, v6
	v_max_u32_e32 v105, v246, v6
	v_cndmask_b32_e64 v246, v105, v104, s[88:89]
	v_min_u32_e32 v106, v248, v7
	v_max_u32_e32 v107, v248, v7
	v_cndmask_b32_e64 v248, v107, v106, s[88:89]
	v_xor_b32_e32 v116, 8, v234
	ds_bpermute_b32 v0, v116, v241
	ds_bpermute_b32 v1, v116, v243
	ds_bpermute_b32 v2, v116, v245
	ds_bpermute_b32 v3, v116, v247
	ds_bpermute_b32 v4, v116, v242
	ds_bpermute_b32 v5, v116, v244
	ds_bpermute_b32 v6, v116, v246
	ds_bpermute_b32 v7, v116, v248
	s_waitcnt lgkmcnt(0)
	s_mov_b32 s88, 0xc3c3c3c3
	s_mov_b32 s89, 0xc3c3c3c3
	v_min_u32_e32 v104, v241, v0
	v_max_u32_e32 v105, v241, v0
	v_cndmask_b32_e64 v241, v105, v104, s[88:89]
	v_min_u32_e32 v106, v243, v1
	v_max_u32_e32 v107, v243, v1
	v_cndmask_b32_e64 v243, v107, v106, s[88:89]
	v_min_u32_e32 v104, v245, v2
	v_max_u32_e32 v105, v245, v2
	v_cndmask_b32_e64 v245, v105, v104, s[88:89]
	v_min_u32_e32 v106, v247, v3
	v_max_u32_e32 v107, v247, v3
	v_cndmask_b32_e64 v247, v107, v106, s[88:89]
	v_min_u32_e32 v104, v242, v4
	v_max_u32_e32 v105, v242, v4
	v_cndmask_b32_e64 v242, v105, v104, s[88:89]
	v_min_u32_e32 v106, v244, v5
	v_max_u32_e32 v107, v244, v5
	v_cndmask_b32_e64 v244, v107, v106, s[88:89]
	v_min_u32_e32 v104, v246, v6
	v_max_u32_e32 v105, v246, v6
	v_cndmask_b32_e64 v246, v105, v104, s[88:89]
	v_min_u32_e32 v106, v248, v7
	v_max_u32_e32 v107, v248, v7
	v_cndmask_b32_e64 v248, v107, v106, s[88:89]
	v_xor_b32_e32 v116, 4, v234
	ds_bpermute_b32 v0, v116, v241
	ds_bpermute_b32 v1, v116, v243
	ds_bpermute_b32 v2, v116, v245
	ds_bpermute_b32 v3, v116, v247
	ds_bpermute_b32 v4, v116, v242
	ds_bpermute_b32 v5, v116, v244
	ds_bpermute_b32 v6, v116, v246
	ds_bpermute_b32 v7, v116, v248
	s_waitcnt lgkmcnt(0)
	s_mov_b32 s88, 0xa5a5a5a5
	s_mov_b32 s89, 0xa5a5a5a5
	v_min_u32_e32 v104, v241, v0
	v_max_u32_e32 v105, v241, v0
	v_cndmask_b32_e64 v241, v105, v104, s[88:89]
	v_min_u32_e32 v106, v243, v1
	v_max_u32_e32 v107, v243, v1
	v_cndmask_b32_e64 v243, v107, v106, s[88:89]
	v_min_u32_e32 v104, v245, v2
	v_max_u32_e32 v105, v245, v2
	v_cndmask_b32_e64 v245, v105, v104, s[88:89]
	v_min_u32_e32 v106, v247, v3
	v_max_u32_e32 v107, v247, v3
	v_cndmask_b32_e64 v247, v107, v106, s[88:89]
	v_min_u32_e32 v104, v242, v4
	v_max_u32_e32 v105, v242, v4
	v_cndmask_b32_e64 v242, v105, v104, s[88:89]
	v_min_u32_e32 v106, v244, v5
	v_max_u32_e32 v107, v244, v5
	v_cndmask_b32_e64 v244, v107, v106, s[88:89]
	v_min_u32_e32 v104, v246, v6
	v_max_u32_e32 v105, v246, v6
	v_cndmask_b32_e64 v246, v105, v104, s[88:89]
	v_min_u32_e32 v106, v248, v7
	v_max_u32_e32 v107, v248, v7
	v_cndmask_b32_e64 v248, v107, v106, s[88:89]
	v_xor_b32_e32 v116, 16, v234
	ds_bpermute_b32 v0, v116, v241
	ds_bpermute_b32 v1, v116, v243
	ds_bpermute_b32 v2, v116, v245
	ds_bpermute_b32 v3, v116, v247
	ds_bpermute_b32 v4, v116, v242
	ds_bpermute_b32 v5, v116, v244
	ds_bpermute_b32 v6, v116, v246
	ds_bpermute_b32 v7, v116, v248
	s_waitcnt lgkmcnt(0)
; DEV void sort_lists(int lane, int& myi0, int& myi1, float& myg0, float& myg1) {
; #pragma unroll
;     for (int k = 2; k <= 128; k <<= 1) {
; #pragma unroll
;       for (int j = k >> 1; j >= 1; j >>= 1) {
;         if (j == 64) {
;           const bool sw_ = myi1 < myi0;
;           const int ti = sw_ ? myi1 : myi0, tj = sw_ ? myi0 : myi1; const float tg = sw_ ? myg1 : myg0, th = sw_ ? myg0 : myg1;
;           myi0 = ti; myi1 = tj; myg0 = tg; myg1 = th;
;         } else {
;           const bool lower = (lane & j) == 0;
;           {
;             const bool up = (k == 128) ? true : ((k == 64) ? true : ((lane & k) == 0));
;             const int oi = __shfl_xor(myi0, j); const float og = __shfl_xor(myg0, j);
;             const bool take = (lower == up) ? (oi < myi0) : (oi > myi0);
;             myi0 = take ? oi : myi0; myg0 = take ? og : myg0;
;           }
;           {
;             const bool up = (k == 128) ? true : ((k == 64) ? false : ((lane & k) == 0));
;             const int oi = __shfl_xor(myi1, j); const float og = __shfl_xor(myg1, j);
;             const bool take = (lower == up) ? (oi < myi1) : (oi > myi1);
;             myi1 = take ? oi : myi1; myg1 = take ? og : myg1;
;           }
;         }
;       }
;     }
; }
	s_mov_b32 s88, 0xf00ff00f
	s_mov_b32 s89, 0xf00ff00f
	v_min_u32_e32 v104, v241, v0
	v_max_u32_e32 v105, v241, v0
	v_cndmask_b32_e64 v241, v105, v104, s[88:89]
	v_min_u32_e32 v106, v243, v1
	v_max_u32_e32 v107, v243, v1
	v_cndmask_b32_e64 v243, v107, v106, s[88:89]
	v_min_u32_e32 v104, v245, v2
	v_max_u32_e32 v105, v245, v2
	v_cndmask_b32_e64 v245, v105, v104, s[88:89]
	v_min_u32_e32 v106, v247, v3
	v_max_u32_e32 v107, v247, v3
	v_cndmask_b32_e64 v247, v107, v106, s[88:89]
	v_min_u32_e32 v104, v242, v4
	v_max_u32_e32 v105, v242, v4
	v_cndmask_b32_e64 v242, v105, v104, s[88:89]
	v_min_u32_e32 v106, v244, v5
	v_max_u32_e32 v107, v244, v5
	v_cndmask_b32_e64 v244, v107, v106, s[88:89]
	v_min_u32_e32 v104, v246, v6
	v_max_u32_e32 v105, v246, v6
	v_cndmask_b32_e64 v246, v105, v104, s[88:89]
	v_min_u32_e32 v106, v248, v7
	v_max_u32_e32 v107, v248, v7
	v_cndmask_b32_e64 v248, v107, v106, s[88:89]
	v_xor_b32_e32 v116, 8, v234
	ds_bpermute_b32 v0, v116, v241
	ds_bpermute_b32 v1, v116, v243
	ds_bpermute_b32 v2, v116, v245
	ds_bpermute_b32 v3, v116, v247
	ds_bpermute_b32 v4, v116, v242
	ds_bpermute_b32 v5, v116, v244
	ds_bpermute_b32 v6, v116, v246
	ds_bpermute_b32 v7, v116, v248
	s_waitcnt lgkmcnt(0)
	s_mov_b32 s88, 0xcc33cc33
	s_mov_b32 s89, 0xcc33cc33
	v_min_u32_e32 v104, v241, v0
	v_max_u32_e32 v105, v241, v0
	v_cndmask_b32_e64 v241, v105, v104, s[88:89]
	v_min_u32_e32 v106, v243, v1
	v_max_u32_e32 v107, v243, v1
	v_cndmask_b32_e64 v243, v107, v106, s[88:89]
	v_min_u32_e32 v104, v245, v2
	v_max_u32_e32 v105, v245, v2
	v_cndmask_b32_e64 v245, v105, v104, s[88:89]
	v_min_u32_e32 v106, v247, v3
	v_max_u32_e32 v107, v247, v3
	v_cndmask_b32_e64 v247, v107, v106, s[88:89]
	v_min_u32_e32 v104, v242, v4
	v_max_u32_e32 v105, v242, v4
	v_cndmask_b32_e64 v242, v105, v104, s[88:89]
	v_min_u32_e32 v106, v244, v5
	v_max_u32_e32 v107, v244, v5
	v_cndmask_b32_e64 v244, v107, v106, s[88:89]
	v_min_u32_e32 v104, v246, v6
	v_max_u32_e32 v105, v246, v6
	v_cndmask_b32_e64 v246, v105, v104, s[88:89]
	v_min_u32_e32 v106, v248, v7
	v_max_u32_e32 v107, v248, v7
	v_cndmask_b32_e64 v248, v107, v106, s[88:89]
	v_xor_b32_e32 v116, 4, v234
	ds_bpermute_b32 v0, v116, v241
	ds_bpermute_b32 v1, v116, v243
	ds_bpermute_b32 v2, v116, v245
	ds_bpermute_b32 v3, v116, v247
	ds_bpermute_b32 v4, v116, v242
	ds_bpermute_b32 v5, v116, v244
	ds_bpermute_b32 v6, v116, v246
	ds_bpermute_b32 v7, v116, v248
	s_waitcnt lgkmcnt(0)
	s_mov_b32 s88, 0xaa55aa55
	s_mov_b32 s89, 0xaa55aa55
	v_min_u32_e32 v104, v241, v0
	v_max_u32_e32 v105, v241, v0
	v_cndmask_b32_e64 v241, v105, v104, s[88:89]
	v_min_u32_e32 v106, v243, v1
	v_max_u32_e32 v107, v243, v1
	v_cndmask_b32_e64 v243, v107, v106, s[88:89]
	v_min_u32_e32 v104, v245, v2
	v_max_u32_e32 v105, v245, v2
	v_cndmask_b32_e64 v245, v105, v104, s[88:89]
	v_min_u32_e32 v106, v247, v3
	v_max_u32_e32 v107, v247, v3
	v_cndmask_b32_e64 v247, v107, v106, s[88:89]
	v_min_u32_e32 v104, v242, v4
	v_max_u32_e32 v105, v242, v4
	v_cndmask_b32_e64 v242, v105, v104, s[88:89]
	v_min_u32_e32 v106, v244, v5
	v_max_u32_e32 v107, v244, v5
	v_cndmask_b32_e64 v244, v107, v106, s[88:89]
	v_min_u32_e32 v104, v246, v6
	v_max_u32_e32 v105, v246, v6
	v_cndmask_b32_e64 v246, v105, v104, s[88:89]
	v_min_u32_e32 v106, v248, v7
	v_max_u32_e32 v107, v248, v7
	v_cndmask_b32_e64 v248, v107, v106, s[88:89]
	v_xor_b32_e32 v116, 32, v234
	ds_bpermute_b32 v0, v116, v241
	ds_bpermute_b32 v1, v116, v243
	ds_bpermute_b32 v2, v116, v245
	ds_bpermute_b32 v3, v116, v247
	ds_bpermute_b32 v4, v116, v242
	ds_bpermute_b32 v5, v116, v244
	ds_bpermute_b32 v6, v116, v246
	ds_bpermute_b32 v7, v116, v248
	s_waitcnt lgkmcnt(0)
	s_mov_b32 s88, 0xff0000ff
	s_mov_b32 s89, 0xff0000ff
	v_min_u32_e32 v104, v241, v0
	v_max_u32_e32 v105, v241, v0
	v_cndmask_b32_e64 v241, v105, v104, s[88:89]
	v_min_u32_e32 v106, v243, v1
	v_max_u32_e32 v107, v243, v1
	v_cndmask_b32_e64 v243, v107, v106, s[88:89]
	v_min_u32_e32 v104, v245, v2
	v_max_u32_e32 v105, v245, v2
	v_cndmask_b32_e64 v245, v105, v104, s[88:89]
	v_min_u32_e32 v106, v247, v3
	v_max_u32_e32 v107, v247, v3
	v_cndmask_b32_e64 v247, v107, v106, s[88:89]
	v_min_u32_e32 v104, v242, v4
	v_max_u32_e32 v105, v242, v4
	v_cndmask_b32_e64 v242, v105, v104, s[88:89]
	v_min_u32_e32 v106, v244, v5
	v_max_u32_e32 v107, v244, v5
	v_cndmask_b32_e64 v244, v107, v106, s[88:89]
	v_min_u32_e32 v104, v246, v6
	v_max_u32_e32 v105, v246, v6
	v_cndmask_b32_e64 v246, v105, v104, s[88:89]
	v_min_u32_e32 v106, v248, v7
	v_max_u32_e32 v107, v248, v7
	v_cndmask_b32_e64 v248, v107, v106, s[88:89]
	v_xor_b32_e32 v116, 16, v234
	ds_bpermute_b32 v0, v116, v241
	ds_bpermute_b32 v1, v116, v243
	ds_bpermute_b32 v2, v116, v245
	ds_bpermute_b32 v3, v116, v247
	ds_bpermute_b32 v4, v116, v242
	ds_bpermute_b32 v5, v116, v244
	ds_bpermute_b32 v6, v116, v246
	ds_bpermute_b32 v7, v116, v248
	s_waitcnt lgkmcnt(0)
	s_mov_b32 s88, 0xf0f00f0f
	s_mov_b32 s89, 0xf0f00f0f
	v_min_u32_e32 v104, v241, v0
	v_max_u32_e32 v105, v241, v0
	v_cndmask_b32_e64 v241, v105, v104, s[88:89]
	v_min_u32_e32 v106, v243, v1
	v_max_u32_e32 v107, v243, v1
	v_cndmask_b32_e64 v243, v107, v106, s[88:89]
	v_min_u32_e32 v104, v245, v2
	v_max_u32_e32 v105, v245, v2
	v_cndmask_b32_e64 v245, v105, v104, s[88:89]
	v_min_u32_e32 v106, v247, v3
	v_max_u32_e32 v107, v247, v3
	v_cndmask_b32_e64 v247, v107, v106, s[88:89]
	v_min_u32_e32 v104, v242, v4
	v_max_u32_e32 v105, v242, v4
	v_cndmask_b32_e64 v242, v105, v104, s[88:89]
	v_min_u32_e32 v106, v244, v5
	v_max_u32_e32 v107, v244, v5
	v_cndmask_b32_e64 v244, v107, v106, s[88:89]
	v_min_u32_e32 v104, v246, v6
	v_max_u32_e32 v105, v246, v6
	v_cndmask_b32_e64 v246, v105, v104, s[88:89]
	v_min_u32_e32 v106, v248, v7
	v_max_u32_e32 v107, v248, v7
	v_cndmask_b32_e64 v248, v107, v106, s[88:89]
	v_xor_b32_e32 v116, 8, v234
	ds_bpermute_b32 v0, v116, v241
	ds_bpermute_b32 v1, v116, v243
	ds_bpermute_b32 v2, v116, v245
	ds_bpermute_b32 v3, v116, v247
	ds_bpermute_b32 v4, v116, v242
	ds_bpermute_b32 v5, v116, v244
	ds_bpermute_b32 v6, v116, v246
	ds_bpermute_b32 v7, v116, v248
	s_waitcnt lgkmcnt(0)
; DEV void sort_lists(int lane, int& myi0, int& myi1, float& myg0, float& myg1) {
; #pragma unroll
;     for (int k = 2; k <= 128; k <<= 1) {
; #pragma unroll
;       for (int j = k >> 1; j >= 1; j >>= 1) {
;         if (j == 64) {
;           const bool sw_ = myi1 < myi0;
;           const int ti = sw_ ? myi1 : myi0, tj = sw_ ? myi0 : myi1; const float tg = sw_ ? myg1 : myg0, th = sw_ ? myg0 : myg1;
;           myi0 = ti; myi1 = tj; myg0 = tg; myg1 = th;
;         } else {
;           const bool lower = (lane & j) == 0;
;           {
;             const bool up = (k == 128) ? true : ((k == 64) ? true : ((lane & k) == 0));
;             const int oi = __shfl_xor(myi0, j); const float og = __shfl_xor(myg0, j);
;             const bool take = (lower == up) ? (oi < myi0) : (oi > myi0);
;             myi0 = take ? oi : myi0; myg0 = take ? og : myg0;
;           }
;           {
;             const bool up = (k == 128) ? true : ((k == 64) ? false : ((lane & k) == 0));
;             const int oi = __shfl_xor(myi1, j); const float og = __shfl_xor(myg1, j);
;             const bool take = (lower == up) ? (oi < myi1) : (oi > myi1);
;             myi1 = take ? oi : myi1; myg1 = take ? og : myg1;
;           }
;         }
;       }
;     }
; }
	s_mov_b32 s88, 0xcccc3333
	s_mov_b32 s89, 0xcccc3333
	v_min_u32_e32 v104, v241, v0
	v_max_u32_e32 v105, v241, v0
	v_cndmask_b32_e64 v241, v105, v104, s[88:89]
	v_min_u32_e32 v106, v243, v1
	v_max_u32_e32 v107, v243, v1
	v_cndmask_b32_e64 v243, v107, v106, s[88:89]
	v_min_u32_e32 v104, v245, v2
	v_max_u32_e32 v105, v245, v2
	v_cndmask_b32_e64 v245, v105, v104, s[88:89]
	v_min_u32_e32 v106, v247, v3
	v_max_u32_e32 v107, v247, v3
	v_cndmask_b32_e64 v247, v107, v106, s[88:89]
	v_min_u32_e32 v104, v242, v4
	v_max_u32_e32 v105, v242, v4
	v_cndmask_b32_e64 v242, v105, v104, s[88:89]
	v_min_u32_e32 v106, v244, v5
	v_max_u32_e32 v107, v244, v5
	v_cndmask_b32_e64 v244, v107, v106, s[88:89]
	v_min_u32_e32 v104, v246, v6
	v_max_u32_e32 v105, v246, v6
	v_cndmask_b32_e64 v246, v105, v104, s[88:89]
	v_min_u32_e32 v106, v248, v7
	v_max_u32_e32 v107, v248, v7
	v_cndmask_b32_e64 v248, v107, v106, s[88:89]
	v_xor_b32_e32 v116, 4, v234
	ds_bpermute_b32 v0, v116, v241
	ds_bpermute_b32 v1, v116, v243
	ds_bpermute_b32 v2, v116, v245
	ds_bpermute_b32 v3, v116, v247
	ds_bpermute_b32 v4, v116, v242
	ds_bpermute_b32 v5, v116, v244
	ds_bpermute_b32 v6, v116, v246
	ds_bpermute_b32 v7, v116, v248
	s_waitcnt lgkmcnt(0)
	s_mov_b32 s88, 0xaaaa5555
	s_mov_b32 s89, 0xaaaa5555
	v_min_u32_e32 v104, v241, v0
	v_max_u32_e32 v105, v241, v0
	v_cndmask_b32_e64 v241, v105, v104, s[88:89]
	v_min_u32_e32 v106, v243, v1
	v_max_u32_e32 v107, v243, v1
	v_cndmask_b32_e64 v243, v107, v106, s[88:89]
	v_min_u32_e32 v104, v245, v2
	v_max_u32_e32 v105, v245, v2
	v_cndmask_b32_e64 v245, v105, v104, s[88:89]
	v_min_u32_e32 v106, v247, v3
	v_max_u32_e32 v107, v247, v3
	v_cndmask_b32_e64 v247, v107, v106, s[88:89]
	v_min_u32_e32 v104, v242, v4
	v_max_u32_e32 v105, v242, v4
	v_cndmask_b32_e64 v242, v105, v104, s[88:89]
	v_min_u32_e32 v106, v244, v5
	v_max_u32_e32 v107, v244, v5
	v_cndmask_b32_e64 v244, v107, v106, s[88:89]
	v_min_u32_e32 v104, v246, v6
	v_max_u32_e32 v105, v246, v6
	v_cndmask_b32_e64 v246, v105, v104, s[88:89]
	v_min_u32_e32 v106, v248, v7
	v_max_u32_e32 v107, v248, v7
	v_cndmask_b32_e64 v248, v107, v106, s[88:89]
	v_xor_b32_e32 v116, 64, v234
	ds_bpermute_b32 v0, v116, v241
	ds_bpermute_b32 v1, v116, v243
	ds_bpermute_b32 v2, v116, v245
	ds_bpermute_b32 v3, v116, v247
	ds_bpermute_b32 v4, v116, v242
	ds_bpermute_b32 v5, v116, v244
	ds_bpermute_b32 v6, v116, v246
	ds_bpermute_b32 v7, v116, v248
	s_waitcnt lgkmcnt(0)
	s_mov_b32 s88, 0xffff
	s_mov_b32 s89, 0xffff0000
	v_min_u32_e32 v104, v241, v0
	v_max_u32_e32 v105, v241, v0
	v_cndmask_b32_e64 v241, v105, v104, s[88:89]
	v_min_u32_e32 v106, v243, v1
	v_max_u32_e32 v107, v243, v1
	v_cndmask_b32_e64 v243, v107, v106, s[88:89]
	v_min_u32_e32 v104, v245, v2
	v_max_u32_e32 v105, v245, v2
	v_cndmask_b32_e64 v245, v105, v104, s[88:89]
	v_min_u32_e32 v106, v247, v3
	v_max_u32_e32 v107, v247, v3
	v_cndmask_b32_e64 v247, v107, v106, s[88:89]
	v_min_u32_e32 v104, v242, v4
	v_max_u32_e32 v105, v242, v4
	v_cndmask_b32_e64 v242, v105, v104, s[88:89]
	v_min_u32_e32 v106, v244, v5
	v_max_u32_e32 v107, v244, v5
	v_cndmask_b32_e64 v244, v107, v106, s[88:89]
	v_min_u32_e32 v104, v246, v6
	v_max_u32_e32 v105, v246, v6
	v_cndmask_b32_e64 v246, v105, v104, s[88:89]
	v_min_u32_e32 v106, v248, v7
	v_max_u32_e32 v107, v248, v7
	v_cndmask_b32_e64 v248, v107, v106, s[88:89]
	v_xor_b32_e32 v116, 32, v234
	ds_bpermute_b32 v0, v116, v241
	ds_bpermute_b32 v1, v116, v243
	ds_bpermute_b32 v2, v116, v245
	ds_bpermute_b32 v3, v116, v247
	ds_bpermute_b32 v4, v116, v242
	ds_bpermute_b32 v5, v116, v244
	ds_bpermute_b32 v6, v116, v246
	ds_bpermute_b32 v7, v116, v248
	s_waitcnt lgkmcnt(0)
	s_mov_b32 s88, 0xff00ff
	s_mov_b32 s89, 0xff00ff00
	v_min_u32_e32 v104, v241, v0
	v_max_u32_e32 v105, v241, v0
	v_cndmask_b32_e64 v241, v105, v104, s[88:89]
	v_min_u32_e32 v106, v243, v1
	v_max_u32_e32 v107, v243, v1
	v_cndmask_b32_e64 v243, v107, v106, s[88:89]
	v_min_u32_e32 v104, v245, v2
	v_max_u32_e32 v105, v245, v2
	v_cndmask_b32_e64 v245, v105, v104, s[88:89]
	v_min_u32_e32 v106, v247, v3
	v_max_u32_e32 v107, v247, v3
	v_cndmask_b32_e64 v247, v107, v106, s[88:89]
	v_min_u32_e32 v104, v242, v4
	v_max_u32_e32 v105, v242, v4
	v_cndmask_b32_e64 v242, v105, v104, s[88:89]
	v_min_u32_e32 v106, v244, v5
	v_max_u32_e32 v107, v244, v5
	v_cndmask_b32_e64 v244, v107, v106, s[88:89]
	v_min_u32_e32 v104, v246, v6
	v_max_u32_e32 v105, v246, v6
	v_cndmask_b32_e64 v246, v105, v104, s[88:89]
	v_min_u32_e32 v106, v248, v7
	v_max_u32_e32 v107, v248, v7
	v_cndmask_b32_e64 v248, v107, v106, s[88:89]
	v_xor_b32_e32 v116, 16, v234
	ds_bpermute_b32 v0, v116, v241
	ds_bpermute_b32 v1, v116, v243
	ds_bpermute_b32 v2, v116, v245
	ds_bpermute_b32 v3, v116, v247
	ds_bpermute_b32 v4, v116, v242
	ds_bpermute_b32 v5, v116, v244
	ds_bpermute_b32 v6, v116, v246
	ds_bpermute_b32 v7, v116, v248
	s_waitcnt lgkmcnt(0)
	s_mov_b32 s88, 0xf0f0f0f
	s_mov_b32 s89, 0xf0f0f0f0
	v_min_u32_e32 v104, v241, v0
	v_max_u32_e32 v105, v241, v0
	v_cndmask_b32_e64 v241, v105, v104, s[88:89]
	v_min_u32_e32 v106, v243, v1
	v_max_u32_e32 v107, v243, v1
	v_cndmask_b32_e64 v243, v107, v106, s[88:89]
	v_min_u32_e32 v104, v245, v2
	v_max_u32_e32 v105, v245, v2
	v_cndmask_b32_e64 v245, v105, v104, s[88:89]
	v_min_u32_e32 v106, v247, v3
	v_max_u32_e32 v107, v247, v3
	v_cndmask_b32_e64 v247, v107, v106, s[88:89]
	v_min_u32_e32 v104, v242, v4
	v_max_u32_e32 v105, v242, v4
	v_cndmask_b32_e64 v242, v105, v104, s[88:89]
	v_min_u32_e32 v106, v244, v5
	v_max_u32_e32 v107, v244, v5
	v_cndmask_b32_e64 v244, v107, v106, s[88:89]
	v_min_u32_e32 v104, v246, v6
	v_max_u32_e32 v105, v246, v6
	v_cndmask_b32_e64 v246, v105, v104, s[88:89]
	v_min_u32_e32 v106, v248, v7
	v_max_u32_e32 v107, v248, v7
	v_cndmask_b32_e64 v248, v107, v106, s[88:89]
	v_xor_b32_e32 v116, 8, v234
	ds_bpermute_b32 v0, v116, v241
	ds_bpermute_b32 v1, v116, v243
	ds_bpermute_b32 v2, v116, v245
	ds_bpermute_b32 v3, v116, v247
	ds_bpermute_b32 v4, v116, v242
	ds_bpermute_b32 v5, v116, v244
	ds_bpermute_b32 v6, v116, v246
	ds_bpermute_b32 v7, v116, v248
	s_waitcnt lgkmcnt(0)
; DEV void sort_lists(int lane, int& myi0, int& myi1, float& myg0, float& myg1) {
; #pragma unroll
;     for (int k = 2; k <= 128; k <<= 1) {
; #pragma unroll
;       for (int j = k >> 1; j >= 1; j >>= 1) {
;         if (j == 64) {
;           const bool sw_ = myi1 < myi0;
;           const int ti = sw_ ? myi1 : myi0, tj = sw_ ? myi0 : myi1; const float tg = sw_ ? myg1 : myg0, th = sw_ ? myg0 : myg1;
;           myi0 = ti; myi1 = tj; myg0 = tg; myg1 = th;
;         } else {
;           const bool lower = (lane & j) == 0;
;           {
;             const bool up = (k == 128) ? true : ((k == 64) ? true : ((lane & k) == 0));
;             const int oi = __shfl_xor(myi0, j); const float og = __shfl_xor(myg0, j);
;             const bool take = (lower == up) ? (oi < myi0) : (oi > myi0);
;             myi0 = take ? oi : myi0; myg0 = take ? og : myg0;
;           }
;           {
;             const bool up = (k == 128) ? true : ((k == 64) ? false : ((lane & k) == 0));
;             const int oi = __shfl_xor(myi1, j); const float og = __shfl_xor(myg1, j);
;             const bool take = (lower == up) ? (oi < myi1) : (oi > myi1);
;             myi1 = take ? oi : myi1; myg1 = take ? og : myg1;
;           }
;         }
;       }
;     }
; }
	s_mov_b32 s88, 0x33333333
	s_mov_b32 s89, 0xcccccccc
	v_min_u32_e32 v104, v241, v0
	v_max_u32_e32 v105, v241, v0
	v_cndmask_b32_e64 v241, v105, v104, s[88:89]
	v_min_u32_e32 v106, v243, v1
	v_max_u32_e32 v107, v243, v1
	v_cndmask_b32_e64 v243, v107, v106, s[88:89]
	v_min_u32_e32 v104, v245, v2
	v_max_u32_e32 v105, v245, v2
	v_cndmask_b32_e64 v245, v105, v104, s[88:89]
	v_min_u32_e32 v106, v247, v3
	v_max_u32_e32 v107, v247, v3
	v_cndmask_b32_e64 v247, v107, v106, s[88:89]
	v_min_u32_e32 v104, v242, v4
	v_max_u32_e32 v105, v242, v4
	v_cndmask_b32_e64 v242, v105, v104, s[88:89]
	v_min_u32_e32 v106, v244, v5
	v_max_u32_e32 v107, v244, v5
	v_cndmask_b32_e64 v244, v107, v106, s[88:89]
	v_min_u32_e32 v104, v246, v6
	v_max_u32_e32 v105, v246, v6
	v_cndmask_b32_e64 v246, v105, v104, s[88:89]
	v_min_u32_e32 v106, v248, v7
	v_max_u32_e32 v107, v248, v7
	v_cndmask_b32_e64 v248, v107, v106, s[88:89]
	v_xor_b32_e32 v116, 4, v234
	ds_bpermute_b32 v0, v116, v241
	ds_bpermute_b32 v1, v116, v243
	ds_bpermute_b32 v2, v116, v245
	ds_bpermute_b32 v3, v116, v247
	ds_bpermute_b32 v4, v116, v242
	ds_bpermute_b32 v5, v116, v244
	ds_bpermute_b32 v6, v116, v246
	ds_bpermute_b32 v7, v116, v248
	s_waitcnt lgkmcnt(0)
	s_mov_b32 s88, 0x55555555
	s_mov_b32 s89, 0xaaaaaaaa
	v_min_u32_e32 v104, v241, v0
	v_max_u32_e32 v105, v241, v0
	v_cndmask_b32_e64 v241, v105, v104, s[88:89]
	v_min_u32_e32 v106, v243, v1
	v_max_u32_e32 v107, v243, v1
	v_cndmask_b32_e64 v243, v107, v106, s[88:89]
	v_min_u32_e32 v104, v245, v2
	v_max_u32_e32 v105, v245, v2
	v_cndmask_b32_e64 v245, v105, v104, s[88:89]
	v_min_u32_e32 v106, v247, v3
	v_max_u32_e32 v107, v247, v3
	v_cndmask_b32_e64 v247, v107, v106, s[88:89]
	v_min_u32_e32 v104, v242, v4
	v_max_u32_e32 v105, v242, v4
	v_cndmask_b32_e64 v242, v105, v104, s[88:89]
	v_min_u32_e32 v106, v244, v5
	v_max_u32_e32 v107, v244, v5
	v_cndmask_b32_e64 v244, v107, v106, s[88:89]
	v_min_u32_e32 v104, v246, v6
	v_max_u32_e32 v105, v246, v6
	v_cndmask_b32_e64 v246, v105, v104, s[88:89]
	v_min_u32_e32 v106, v248, v7
	v_max_u32_e32 v107, v248, v7
	v_cndmask_b32_e64 v248, v107, v106, s[88:89]
	v_xor_b32_e32 v116, 128, v234
	ds_bpermute_b32 v0, v116, v241
	ds_bpermute_b32 v1, v116, v243
	ds_bpermute_b32 v2, v116, v245
	ds_bpermute_b32 v3, v116, v247
	ds_bpermute_b32 v4, v116, v242
	ds_bpermute_b32 v5, v116, v244
	ds_bpermute_b32 v6, v116, v246
	ds_bpermute_b32 v7, v116, v248
	s_waitcnt lgkmcnt(0)
	s_mov_b32 s88, 0xffffffff
	s_mov_b32 s89, 0x0
	v_min_u32_e32 v104, v241, v0
	v_max_u32_e32 v105, v241, v0
	v_cndmask_b32_e64 v241, v105, v104, s[88:89]
	v_min_u32_e32 v106, v243, v1
	v_max_u32_e32 v107, v243, v1
	v_cndmask_b32_e64 v243, v107, v106, s[88:89]
	v_min_u32_e32 v104, v245, v2
	v_max_u32_e32 v105, v245, v2
	v_cndmask_b32_e64 v245, v105, v104, s[88:89]
	v_min_u32_e32 v106, v247, v3
	v_max_u32_e32 v107, v247, v3
	v_cndmask_b32_e64 v247, v107, v106, s[88:89]
	s_mov_b32 s88, 0x0
	s_mov_b32 s89, 0xffffffff
	v_min_u32_e32 v104, v242, v4
	v_max_u32_e32 v105, v242, v4
	v_cndmask_b32_e64 v242, v105, v104, s[88:89]
	v_min_u32_e32 v106, v244, v5
	v_max_u32_e32 v107, v244, v5
	v_cndmask_b32_e64 v244, v107, v106, s[88:89]
	v_min_u32_e32 v104, v246, v6
	v_max_u32_e32 v105, v246, v6
	v_cndmask_b32_e64 v246, v105, v104, s[88:89]
	v_min_u32_e32 v106, v248, v7
	v_max_u32_e32 v107, v248, v7
	v_cndmask_b32_e64 v248, v107, v106, s[88:89]
	v_xor_b32_e32 v116, 64, v234
	ds_bpermute_b32 v0, v116, v241
	ds_bpermute_b32 v1, v116, v243
	ds_bpermute_b32 v2, v116, v245
	ds_bpermute_b32 v3, v116, v247
	ds_bpermute_b32 v4, v116, v242
	ds_bpermute_b32 v5, v116, v244
	ds_bpermute_b32 v6, v116, v246
	ds_bpermute_b32 v7, v116, v248
	s_waitcnt lgkmcnt(0)
	s_mov_b32 s88, 0xffff
	s_mov_b32 s89, 0xffff
	v_min_u32_e32 v104, v241, v0
	v_max_u32_e32 v105, v241, v0
	v_cndmask_b32_e64 v241, v105, v104, s[88:89]
	v_min_u32_e32 v106, v243, v1
	v_max_u32_e32 v107, v243, v1
	v_cndmask_b32_e64 v243, v107, v106, s[88:89]
	v_min_u32_e32 v104, v245, v2
	v_max_u32_e32 v105, v245, v2
	v_cndmask_b32_e64 v245, v105, v104, s[88:89]
	v_min_u32_e32 v106, v247, v3
	v_max_u32_e32 v107, v247, v3
	v_cndmask_b32_e64 v247, v107, v106, s[88:89]
	s_mov_b32 s88, 0xffff0000
	s_mov_b32 s89, 0xffff0000
	v_min_u32_e32 v104, v242, v4
	v_max_u32_e32 v105, v242, v4
	v_cndmask_b32_e64 v242, v105, v104, s[88:89]
	v_min_u32_e32 v106, v244, v5
	v_max_u32_e32 v107, v244, v5
	v_cndmask_b32_e64 v244, v107, v106, s[88:89]
	v_min_u32_e32 v104, v246, v6
	v_max_u32_e32 v105, v246, v6
	v_cndmask_b32_e64 v246, v105, v104, s[88:89]
	v_min_u32_e32 v106, v248, v7
	v_max_u32_e32 v107, v248, v7
	v_cndmask_b32_e64 v248, v107, v106, s[88:89]
	v_xor_b32_e32 v116, 32, v234
	ds_bpermute_b32 v0, v116, v241
	ds_bpermute_b32 v1, v116, v243
	ds_bpermute_b32 v2, v116, v245
	ds_bpermute_b32 v3, v116, v247
	ds_bpermute_b32 v4, v116, v242
	ds_bpermute_b32 v5, v116, v244
	ds_bpermute_b32 v6, v116, v246
	ds_bpermute_b32 v7, v116, v248
	s_waitcnt lgkmcnt(0)
	s_mov_b32 s88, 0xff00ff
	s_mov_b32 s89, 0xff00ff
	v_min_u32_e32 v104, v241, v0
	v_max_u32_e32 v105, v241, v0
	v_cndmask_b32_e64 v241, v105, v104, s[88:89]
	v_min_u32_e32 v106, v243, v1
	v_max_u32_e32 v107, v243, v1
	v_cndmask_b32_e64 v243, v107, v106, s[88:89]
	v_min_u32_e32 v104, v245, v2
	v_max_u32_e32 v105, v245, v2
	v_cndmask_b32_e64 v245, v105, v104, s[88:89]
	v_min_u32_e32 v106, v247, v3
	v_max_u32_e32 v107, v247, v3
	v_cndmask_b32_e64 v247, v107, v106, s[88:89]
	s_mov_b32 s88, 0xff00ff00
	s_mov_b32 s89, 0xff00ff00
	v_min_u32_e32 v104, v242, v4
	v_max_u32_e32 v105, v242, v4
	v_cndmask_b32_e64 v242, v105, v104, s[88:89]
	v_min_u32_e32 v106, v244, v5
	v_max_u32_e32 v107, v244, v5
	v_cndmask_b32_e64 v244, v107, v106, s[88:89]
	v_min_u32_e32 v104, v246, v6
	v_max_u32_e32 v105, v246, v6
	v_cndmask_b32_e64 v246, v105, v104, s[88:89]
	v_min_u32_e32 v106, v248, v7
	v_max_u32_e32 v107, v248, v7
	v_cndmask_b32_e64 v248, v107, v106, s[88:89]
	v_xor_b32_e32 v116, 16, v234
	ds_bpermute_b32 v0, v116, v241
	ds_bpermute_b32 v1, v116, v243
	ds_bpermute_b32 v2, v116, v245
	ds_bpermute_b32 v3, v116, v247
	ds_bpermute_b32 v4, v116, v242
	ds_bpermute_b32 v5, v116, v244
	ds_bpermute_b32 v6, v116, v246
	ds_bpermute_b32 v7, v116, v248
	s_waitcnt lgkmcnt(0)
; DEV void sort_lists(int lane, int& myi0, int& myi1, float& myg0, float& myg1) {
; #pragma unroll
;     for (int k = 2; k <= 128; k <<= 1) {
; #pragma unroll
;       for (int j = k >> 1; j >= 1; j >>= 1) {
;         if (j == 64) {
;           const bool sw_ = myi1 < myi0;
;           const int ti = sw_ ? myi1 : myi0, tj = sw_ ? myi0 : myi1; const float tg = sw_ ? myg1 : myg0, th = sw_ ? myg0 : myg1;
;           myi0 = ti; myi1 = tj; myg0 = tg; myg1 = th;
;         } else {
;           const bool lower = (lane & j) == 0;
;           {
;             const bool up = (k == 128) ? true : ((k == 64) ? true : ((lane & k) == 0));
;             const int oi = __shfl_xor(myi0, j); const float og = __shfl_xor(myg0, j);
;             const bool take = (lower == up) ? (oi < myi0) : (oi > myi0);
;             myi0 = take ? oi : myi0; myg0 = take ? og : myg0;
;           }
;           {
;             const bool up = (k == 128) ? true : ((k == 64) ? false : ((lane & k) == 0));
;             const int oi = __shfl_xor(myi1, j); const float og = __shfl_xor(myg1, j);
;             const bool take = (lower == up) ? (oi < myi1) : (oi > myi1);
;             myi1 = take ? oi : myi1; myg1 = take ? og : myg1;
;           }
;         }
;       }
;     }
; }
	s_mov_b32 s88, 0xf0f0f0f
	s_mov_b32 s89, 0xf0f0f0f
	v_min_u32_e32 v104, v241, v0
	v_max_u32_e32 v105, v241, v0
	v_cndmask_b32_e64 v241, v105, v104, s[88:89]
	v_min_u32_e32 v106, v243, v1
	v_max_u32_e32 v107, v243, v1
	v_cndmask_b32_e64 v243, v107, v106, s[88:89]
	v_min_u32_e32 v104, v245, v2
	v_max_u32_e32 v105, v245, v2
	v_cndmask_b32_e64 v245, v105, v104, s[88:89]
	v_min_u32_e32 v106, v247, v3
	v_max_u32_e32 v107, v247, v3
	v_cndmask_b32_e64 v247, v107, v106, s[88:89]
	s_mov_b32 s88, 0xf0f0f0f0
	s_mov_b32 s89, 0xf0f0f0f0
	v_min_u32_e32 v104, v242, v4
	v_max_u32_e32 v105, v242, v4
	v_cndmask_b32_e64 v242, v105, v104, s[88:89]
	v_min_u32_e32 v106, v244, v5
	v_max_u32_e32 v107, v244, v5
	v_cndmask_b32_e64 v244, v107, v106, s[88:89]
	v_min_u32_e32 v104, v246, v6
	v_max_u32_e32 v105, v246, v6
	v_cndmask_b32_e64 v246, v105, v104, s[88:89]
	v_min_u32_e32 v106, v248, v7
	v_max_u32_e32 v107, v248, v7
	v_cndmask_b32_e64 v248, v107, v106, s[88:89]
	v_xor_b32_e32 v116, 8, v234
	ds_bpermute_b32 v0, v116, v241
	ds_bpermute_b32 v1, v116, v243
	ds_bpermute_b32 v2, v116, v245
	ds_bpermute_b32 v3, v116, v247
	ds_bpermute_b32 v4, v116, v242
	ds_bpermute_b32 v5, v116, v244
	ds_bpermute_b32 v6, v116, v246
	ds_bpermute_b32 v7, v116, v248
	s_waitcnt lgkmcnt(0)
	s_mov_b32 s88, 0x33333333
	s_mov_b32 s89, 0x33333333
	v_min_u32_e32 v104, v241, v0
	v_max_u32_e32 v105, v241, v0
	v_cndmask_b32_e64 v241, v105, v104, s[88:89]
	v_min_u32_e32 v106, v243, v1
	v_max_u32_e32 v107, v243, v1
	v_cndmask_b32_e64 v243, v107, v106, s[88:89]
	v_min_u32_e32 v104, v245, v2
	v_max_u32_e32 v105, v245, v2
	v_cndmask_b32_e64 v245, v105, v104, s[88:89]
	v_min_u32_e32 v106, v247, v3
	v_max_u32_e32 v107, v247, v3
	v_cndmask_b32_e64 v247, v107, v106, s[88:89]
	s_mov_b32 s88, 0xcccccccc
	s_mov_b32 s89, 0xcccccccc
	v_min_u32_e32 v104, v242, v4
	v_max_u32_e32 v105, v242, v4
	v_cndmask_b32_e64 v242, v105, v104, s[88:89]
	v_min_u32_e32 v106, v244, v5
	v_max_u32_e32 v107, v244, v5
	v_cndmask_b32_e64 v244, v107, v106, s[88:89]
	v_min_u32_e32 v104, v246, v6
	v_max_u32_e32 v105, v246, v6
	v_cndmask_b32_e64 v246, v105, v104, s[88:89]
	v_min_u32_e32 v106, v248, v7
	v_max_u32_e32 v107, v248, v7
	v_cndmask_b32_e64 v248, v107, v106, s[88:89]
	v_xor_b32_e32 v116, 4, v234
	ds_bpermute_b32 v0, v116, v241
	ds_bpermute_b32 v1, v116, v243
	ds_bpermute_b32 v2, v116, v245
	ds_bpermute_b32 v3, v116, v247
	ds_bpermute_b32 v4, v116, v242
	ds_bpermute_b32 v5, v116, v244
	ds_bpermute_b32 v6, v116, v246
	ds_bpermute_b32 v7, v116, v248
	s_waitcnt lgkmcnt(0)
	s_mov_b32 s88, 0x55555555
	s_mov_b32 s89, 0x55555555
	v_min_u32_e32 v104, v241, v0
	v_max_u32_e32 v105, v241, v0
	v_cndmask_b32_e64 v241, v105, v104, s[88:89]
	v_min_u32_e32 v106, v243, v1
	v_max_u32_e32 v107, v243, v1
	v_cndmask_b32_e64 v243, v107, v106, s[88:89]
	v_min_u32_e32 v104, v245, v2
	v_max_u32_e32 v105, v245, v2
	v_cndmask_b32_e64 v245, v105, v104, s[88:89]
	v_min_u32_e32 v106, v247, v3
	v_max_u32_e32 v107, v247, v3
	v_cndmask_b32_e64 v247, v107, v106, s[88:89]
	s_mov_b32 s88, 0xaaaaaaaa
	s_mov_b32 s89, 0xaaaaaaaa
	v_min_u32_e32 v104, v242, v4
	v_max_u32_e32 v105, v242, v4
	v_cndmask_b32_e64 v242, v105, v104, s[88:89]
	v_min_u32_e32 v106, v244, v5
	v_max_u32_e32 v107, v244, v5
	v_cndmask_b32_e64 v244, v107, v106, s[88:89]
	v_min_u32_e32 v104, v246, v6
	v_max_u32_e32 v105, v246, v6
	v_cndmask_b32_e64 v246, v105, v104, s[88:89]
	v_min_u32_e32 v106, v248, v7
	v_max_u32_e32 v107, v248, v7
	v_cndmask_b32_e64 v248, v107, v106, s[88:89]
	v_min_u32_e32 v104, v241, v242
	v_max_u32_e32 v242, v241, v242
	v_mov_b32_e32 v241, v104
	v_min_u32_e32 v106, v243, v244
	v_max_u32_e32 v244, v243, v244
	v_mov_b32_e32 v243, v106
	v_min_u32_e32 v104, v245, v246
	v_max_u32_e32 v246, v245, v246
	v_mov_b32_e32 v245, v104
	v_min_u32_e32 v106, v247, v248
	v_max_u32_e32 v248, v247, v248
	v_mov_b32_e32 v247, v106
	v_xor_b32_e32 v116, 128, v234
	ds_bpermute_b32 v0, v116, v241
	ds_bpermute_b32 v1, v116, v243
	ds_bpermute_b32 v2, v116, v245
	ds_bpermute_b32 v3, v116, v247
	ds_bpermute_b32 v4, v116, v242
	ds_bpermute_b32 v5, v116, v244
	ds_bpermute_b32 v6, v116, v246
	ds_bpermute_b32 v7, v116, v248
	s_waitcnt lgkmcnt(0)
	s_mov_b32 s88, 0xffffffff
	s_mov_b32 s89, 0x0
	v_min_u32_e32 v104, v241, v0
	v_max_u32_e32 v105, v241, v0
	v_cndmask_b32_e64 v241, v105, v104, s[88:89]
	v_min_u32_e32 v106, v243, v1
	v_max_u32_e32 v107, v243, v1
	v_cndmask_b32_e64 v243, v107, v106, s[88:89]
	v_min_u32_e32 v104, v245, v2
	v_max_u32_e32 v105, v245, v2
	v_cndmask_b32_e64 v245, v105, v104, s[88:89]
	v_min_u32_e32 v106, v247, v3
	v_max_u32_e32 v107, v247, v3
	v_cndmask_b32_e64 v247, v107, v106, s[88:89]
	v_min_u32_e32 v104, v242, v4
	v_max_u32_e32 v105, v242, v4
	v_cndmask_b32_e64 v242, v105, v104, s[88:89]
	v_min_u32_e32 v106, v244, v5
	v_max_u32_e32 v107, v244, v5
	v_cndmask_b32_e64 v244, v107, v106, s[88:89]
	v_min_u32_e32 v104, v246, v6
	v_max_u32_e32 v105, v246, v6
	v_cndmask_b32_e64 v246, v105, v104, s[88:89]
	v_min_u32_e32 v106, v248, v7
	v_max_u32_e32 v107, v248, v7
	v_cndmask_b32_e64 v248, v107, v106, s[88:89]
	v_xor_b32_e32 v116, 64, v234
	ds_bpermute_b32 v0, v116, v241
	ds_bpermute_b32 v1, v116, v243
	ds_bpermute_b32 v2, v116, v245
	ds_bpermute_b32 v3, v116, v247
	ds_bpermute_b32 v4, v116, v242
	ds_bpermute_b32 v5, v116, v244
	ds_bpermute_b32 v6, v116, v246
	ds_bpermute_b32 v7, v116, v248
	s_waitcnt lgkmcnt(0)
; DEV void sort_lists(int lane, int& myi0, int& myi1, float& myg0, float& myg1) {
; #pragma unroll
;     for (int k = 2; k <= 128; k <<= 1) {
; #pragma unroll
;       for (int j = k >> 1; j >= 1; j >>= 1) {
;         if (j == 64) {
;           const bool sw_ = myi1 < myi0;
;           const int ti = sw_ ? myi1 : myi0, tj = sw_ ? myi0 : myi1; const float tg = sw_ ? myg1 : myg0, th = sw_ ? myg0 : myg1;
;           myi0 = ti; myi1 = tj; myg0 = tg; myg1 = th;
;         } else {
;           const bool lower = (lane & j) == 0;
;           {
;             const bool up = (k == 128) ? true : ((k == 64) ? true : ((lane & k) == 0));
;             const int oi = __shfl_xor(myi0, j); const float og = __shfl_xor(myg0, j);
;             const bool take = (lower == up) ? (oi < myi0) : (oi > myi0);
;             myi0 = take ? oi : myi0; myg0 = take ? og : myg0;
;           }
;           {
;             const bool up = (k == 128) ? true : ((k == 64) ? false : ((lane & k) == 0));
;             const int oi = __shfl_xor(myi1, j); const float og = __shfl_xor(myg1, j);
;             const bool take = (lower == up) ? (oi < myi1) : (oi > myi1);
;             myi1 = take ? oi : myi1; myg1 = take ? og : myg1;
;           }
;         }
;       }
;     }
; }
	s_mov_b32 s88, 0xffff
	s_mov_b32 s89, 0xffff
	v_min_u32_e32 v104, v241, v0
	v_max_u32_e32 v105, v241, v0
	v_cndmask_b32_e64 v241, v105, v104, s[88:89]
	v_min_u32_e32 v106, v243, v1
	v_max_u32_e32 v107, v243, v1
	v_cndmask_b32_e64 v243, v107, v106, s[88:89]
	v_min_u32_e32 v104, v245, v2
	v_max_u32_e32 v105, v245, v2
	v_cndmask_b32_e64 v245, v105, v104, s[88:89]
	v_min_u32_e32 v106, v247, v3
	v_max_u32_e32 v107, v247, v3
	v_cndmask_b32_e64 v247, v107, v106, s[88:89]
	v_min_u32_e32 v104, v242, v4
	v_max_u32_e32 v105, v242, v4
	v_cndmask_b32_e64 v242, v105, v104, s[88:89]
	v_min_u32_e32 v106, v244, v5
	v_max_u32_e32 v107, v244, v5
	v_cndmask_b32_e64 v244, v107, v106, s[88:89]
	v_min_u32_e32 v104, v246, v6
	v_max_u32_e32 v105, v246, v6
	v_cndmask_b32_e64 v246, v105, v104, s[88:89]
	v_min_u32_e32 v106, v248, v7
	v_max_u32_e32 v107, v248, v7
	v_cndmask_b32_e64 v248, v107, v106, s[88:89]
	v_xor_b32_e32 v116, 32, v234
	ds_bpermute_b32 v0, v116, v241
	ds_bpermute_b32 v1, v116, v243
	ds_bpermute_b32 v2, v116, v245
	ds_bpermute_b32 v3, v116, v247
	ds_bpermute_b32 v4, v116, v242
	ds_bpermute_b32 v5, v116, v244
	ds_bpermute_b32 v6, v116, v246
	ds_bpermute_b32 v7, v116, v248
	s_waitcnt lgkmcnt(0)
	s_mov_b32 s88, 0xff00ff
	s_mov_b32 s89, 0xff00ff
	v_min_u32_e32 v104, v241, v0
	v_max_u32_e32 v105, v241, v0
	v_cndmask_b32_e64 v241, v105, v104, s[88:89]
	v_min_u32_e32 v106, v243, v1
	v_max_u32_e32 v107, v243, v1
	v_cndmask_b32_e64 v243, v107, v106, s[88:89]
	v_min_u32_e32 v104, v245, v2
	v_max_u32_e32 v105, v245, v2
	v_cndmask_b32_e64 v245, v105, v104, s[88:89]
	v_min_u32_e32 v106, v247, v3
	v_max_u32_e32 v107, v247, v3
	v_cndmask_b32_e64 v247, v107, v106, s[88:89]
	v_min_u32_e32 v104, v242, v4
	v_max_u32_e32 v105, v242, v4
	v_cndmask_b32_e64 v242, v105, v104, s[88:89]
	v_min_u32_e32 v106, v244, v5
	v_max_u32_e32 v107, v244, v5
	v_cndmask_b32_e64 v244, v107, v106, s[88:89]
	v_min_u32_e32 v104, v246, v6
	v_max_u32_e32 v105, v246, v6
	v_cndmask_b32_e64 v246, v105, v104, s[88:89]
	v_min_u32_e32 v106, v248, v7
	v_max_u32_e32 v107, v248, v7
	v_cndmask_b32_e64 v248, v107, v106, s[88:89]
	v_xor_b32_e32 v116, 16, v234
	ds_bpermute_b32 v0, v116, v241
	ds_bpermute_b32 v1, v116, v243
	ds_bpermute_b32 v2, v116, v245
	ds_bpermute_b32 v3, v116, v247
	ds_bpermute_b32 v4, v116, v242
	ds_bpermute_b32 v5, v116, v244
	ds_bpermute_b32 v6, v116, v246
	ds_bpermute_b32 v7, v116, v248
	s_waitcnt lgkmcnt(0)
	s_mov_b32 s88, 0xf0f0f0f
	s_mov_b32 s89, 0xf0f0f0f
	v_min_u32_e32 v104, v241, v0
	v_max_u32_e32 v105, v241, v0
	v_cndmask_b32_e64 v241, v105, v104, s[88:89]
	v_min_u32_e32 v106, v243, v1
	v_max_u32_e32 v107, v243, v1
	v_cndmask_b32_e64 v243, v107, v106, s[88:89]
	v_min_u32_e32 v104, v245, v2
	v_max_u32_e32 v105, v245, v2
	v_cndmask_b32_e64 v245, v105, v104, s[88:89]
	v_min_u32_e32 v106, v247, v3
	v_max_u32_e32 v107, v247, v3
	v_cndmask_b32_e64 v247, v107, v106, s[88:89]
	v_min_u32_e32 v104, v242, v4
	v_max_u32_e32 v105, v242, v4
	v_cndmask_b32_e64 v242, v105, v104, s[88:89]
	v_min_u32_e32 v106, v244, v5
	v_max_u32_e32 v107, v244, v5
	v_cndmask_b32_e64 v244, v107, v106, s[88:89]
	v_min_u32_e32 v104, v246, v6
	v_max_u32_e32 v105, v246, v6
	v_cndmask_b32_e64 v246, v105, v104, s[88:89]
	v_min_u32_e32 v106, v248, v7
	v_max_u32_e32 v107, v248, v7
	v_cndmask_b32_e64 v248, v107, v106, s[88:89]
	v_xor_b32_e32 v116, 8, v234
	ds_bpermute_b32 v0, v116, v241
	ds_bpermute_b32 v1, v116, v243
	ds_bpermute_b32 v2, v116, v245
	ds_bpermute_b32 v3, v116, v247
	ds_bpermute_b32 v4, v116, v242
	ds_bpermute_b32 v5, v116, v244
	ds_bpermute_b32 v6, v116, v246
	ds_bpermute_b32 v7, v116, v248
	s_waitcnt lgkmcnt(0)
	s_mov_b32 s88, 0x33333333
	s_mov_b32 s89, 0x33333333
	v_min_u32_e32 v104, v241, v0
	v_max_u32_e32 v105, v241, v0
	v_cndmask_b32_e64 v241, v105, v104, s[88:89]
	v_min_u32_e32 v106, v243, v1
	v_max_u32_e32 v107, v243, v1
	v_cndmask_b32_e64 v243, v107, v106, s[88:89]
	v_min_u32_e32 v104, v245, v2
	v_max_u32_e32 v105, v245, v2
	v_cndmask_b32_e64 v245, v105, v104, s[88:89]
	v_min_u32_e32 v106, v247, v3
	v_max_u32_e32 v107, v247, v3
	v_cndmask_b32_e64 v247, v107, v106, s[88:89]
	v_min_u32_e32 v104, v242, v4
	v_max_u32_e32 v105, v242, v4
	v_cndmask_b32_e64 v242, v105, v104, s[88:89]
	v_min_u32_e32 v106, v244, v5
	v_max_u32_e32 v107, v244, v5
	v_cndmask_b32_e64 v244, v107, v106, s[88:89]
	v_min_u32_e32 v104, v246, v6
	v_max_u32_e32 v105, v246, v6
	v_cndmask_b32_e64 v246, v105, v104, s[88:89]
	v_min_u32_e32 v106, v248, v7
	v_max_u32_e32 v107, v248, v7
	v_cndmask_b32_e64 v248, v107, v106, s[88:89]
	v_xor_b32_e32 v116, 4, v234
	ds_bpermute_b32 v0, v116, v241
	ds_bpermute_b32 v1, v116, v243
	ds_bpermute_b32 v2, v116, v245
	ds_bpermute_b32 v3, v116, v247
	ds_bpermute_b32 v4, v116, v242
	ds_bpermute_b32 v5, v116, v244
	ds_bpermute_b32 v6, v116, v246
	ds_bpermute_b32 v7, v116, v248
	s_waitcnt lgkmcnt(0)
; #define PG_ISSUE(BUF, TAB, e0_) do { const int isrc_ = ((e0_) < 64) ? myi0 : myi1; \
;       _Pragma("unroll") for (int e = 0; e < 8; ++e) { const int idx_ = __builtin_amdgcn_readlane(isrc_, ((e0_) + e) & 63); \
;         BUF[e] = *(const u32x4*)((TAB) + (size_t)idx_ * 1024 + lane * 16); } } while (0)
; DEV void sort_lists(int lane, int& myi0, int& myi1, float& myg0, float& myg1) {
;     ...
;           const bool lower = (lane & j) == 0;
;           {
;             const bool up = (k == 128) ? true : ((k == 64) ? true : ((lane & k) == 0));
;             const int oi = __shfl_xor(myi0, j); const float og = __shfl_xor(myg0, j);
;             const bool take = (lower == up) ? (oi < myi0) : (oi > myi0);
;             myi0 = take ? oi : myi0; myg0 = take ? og : myg0;
;           }
;           {
;             const bool up = (k == 128) ? true : ((k == 64) ? false : ((lane & k) == 0));
;             const int oi = __shfl_xor(myi1, j); const float og = __shfl_xor(myg1, j);
;             const bool take = (lower == up) ? (oi < myi1) : (oi > myi1);
;             myi1 = take ? oi : myi1; myg1 = take ? og : myg1;
;           }
;         }
;       }
;     }
; }
; DEV void peer_gather(const Params& P, int l, int m0, const int* idxs, const float* gs) {
;     ...
;     PG_ISSUE(b0, U, 0);
; #pragma nounroll
;     for (int e0 = 0; e0 < 128; e0 += 16) {
;       PG_ISSUE(b1, U, e0 + 8);
	s_mov_b32 s88, 0x55555555
	s_mov_b32 s89, 0x55555555
	v_min_u32_e32 v104, v241, v0
	v_max_u32_e32 v105, v241, v0
	v_cndmask_b32_e64 v241, v105, v104, s[88:89]
	v_min_u32_e32 v106, v243, v1
	v_max_u32_e32 v107, v243, v1
	v_cndmask_b32_e64 v243, v107, v106, s[88:89]
	v_min_u32_e32 v104, v245, v2
	v_max_u32_e32 v105, v245, v2
	v_cndmask_b32_e64 v245, v105, v104, s[88:89]
	v_min_u32_e32 v106, v247, v3
	v_max_u32_e32 v107, v247, v3
	v_cndmask_b32_e64 v247, v107, v106, s[88:89]
	v_min_u32_e32 v104, v242, v4
	v_max_u32_e32 v105, v242, v4
	v_cndmask_b32_e64 v242, v105, v104, s[88:89]
	v_min_u32_e32 v106, v244, v5
	v_max_u32_e32 v107, v244, v5
	v_cndmask_b32_e64 v244, v107, v106, s[88:89]
	v_min_u32_e32 v104, v246, v6
	v_max_u32_e32 v105, v246, v6
	v_cndmask_b32_e64 v246, v105, v104, s[88:89]
	v_min_u32_e32 v106, v248, v7
	v_max_u32_e32 v107, v248, v7
	v_cndmask_b32_e64 v248, v107, v106, s[88:89]
	v_mov_b32_e32 v117, 0
	s_lshl_b32 s98, s2, 11
	s_add_u32 s98, s98, s101
	v_add_u32_e32 v116, s98, v234
	v_and_b32_e32 v144, 0x7f, v241
	v_and_b32_e32 v241, 0xffffff80, v241
	v_lshl_or_b32 v241, v241, 3, v144
	ds_write_b32 v116, v241 offset:0
	v_and_b32_e32 v145, 0x7f, v242
	v_and_b32_e32 v242, 0xffffff80, v242
	v_lshl_or_b32 v242, v242, 3, v145
	ds_write_b32 v116, v242 offset:256
	v_and_b32_e32 v146, 0x7f, v243
	v_and_b32_e32 v243, 0xffffff80, v243
	v_lshl_or_b32 v243, v243, 3, v146
	ds_write_b32 v116, v243 offset:512
	v_and_b32_e32 v147, 0x7f, v244
	v_and_b32_e32 v244, 0xffffff80, v244
	v_lshl_or_b32 v244, v244, 3, v147
	ds_write_b32 v116, v244 offset:768
	v_and_b32_e32 v148, 0x7f, v245
	v_and_b32_e32 v245, 0xffffff80, v245
	v_lshl_or_b32 v245, v245, 3, v148
	ds_write_b32 v116, v245 offset:1024
	v_and_b32_e32 v149, 0x7f, v246
	v_and_b32_e32 v246, 0xffffff80, v246
	v_lshl_or_b32 v246, v246, 3, v149
	ds_write_b32 v116, v246 offset:1280
	v_and_b32_e32 v150, 0x7f, v247
	v_and_b32_e32 v247, 0xffffff80, v247
	v_lshl_or_b32 v247, v247, 3, v150
	ds_write_b32 v116, v247 offset:1536
	v_and_b32_e32 v151, 0x7f, v248
	v_and_b32_e32 v248, 0xffffff80, v248
	v_lshl_or_b32 v248, v248, 3, v151
	ds_write_b32 v116, v248 offset:1792
	v_add_u32_e32 v118, 0x10000, v116
	ds_write_b32 v118, v117 offset:0
	ds_write_b32 v118, v117 offset:256
	ds_write_b32 v118, v117 offset:512
	ds_write_b32 v118, v117 offset:768
	ds_write_b32 v118, v117 offset:1024
	ds_write_b32 v118, v117 offset:1280
	ds_write_b32 v118, v117 offset:1536
	ds_write_b32 v118, v117 offset:1792
	s_add_u32 s2, s2, 1
	s_cmp_lt_u32 s2, 4
	s_cbranch_scc1 .Lpg0_p0
	s_waitcnt lgkmcnt(0)
	v_readfirstlane_b32 s80, v124
	v_readfirstlane_b32 s81, v125
	s_nop 4
	s_mov_b32 s90, 0xfffffc00
	s_mov_b32 s100, 0
	s_mov_b32 s98, 0
	s_mov_b32 s99, 0
	v_readfirstlane_b32 s82, v128
	v_readfirstlane_b32 s83, v129
	s_nop 4
	s_add_u32 vcc_lo, s3, s98
	s_lshl_b32 vcc_lo, vcc_lo, 11
	s_lshl_b32 vcc_hi, s99, 8
	s_add_u32 vcc_lo, vcc_lo, vcc_hi
	v_add_u32_e32 v119, vcc_lo, v236
	global_load_dwordx4 v[80:83], v119, s[82:83]
	global_load_dwordx4 v[84:87], v119, s[82:83] offset:16
	s_lshl_b32 vcc_lo, s98, 9
	s_add_u32 vcc_lo, vcc_lo, s101
	v_add_u32_e32 v116, vcc_lo, v234
	ds_read_b32 v134, v116
	ds_read_b32 v135, v116 offset:256
	s_lshl_b32 vcc_lo, s99, 7
	v_add_u32_e32 v240, vcc_lo, v235
	s_waitcnt lgkmcnt(0)
	ds_bpermute_b32 v142, v249, v134
	ds_bpermute_b32 v143, v250, v134
	s_waitcnt lgkmcnt(0)
	v_and_or_b32 v142, v142, s90, v240
	v_and_or_b32 v143, v143, s90, v240
	global_load_dwordx4 v[0:3], v142, s[80:81]
	global_load_dwordx4 v[4:7], v143, s[80:81]
	ds_bpermute_b32 v142, v251, v134
	ds_bpermute_b32 v143, v252, v134
	s_waitcnt lgkmcnt(0)
	v_and_or_b32 v142, v142, s90, v240
	v_and_or_b32 v143, v143, s90, v240
	global_load_dwordx4 v[8:11], v142, s[80:81]
	global_load_dwordx4 v[12:15], v143, s[80:81]
	ds_bpermute_b32 v142, v253, v134
	ds_bpermute_b32 v143, v254, v134
	s_waitcnt lgkmcnt(0)
	v_and_or_b32 v142, v142, s90, v240
	v_and_or_b32 v143, v143, s90, v240
	global_load_dwordx4 v[16:19], v142, s[80:81]
	global_load_dwordx4 v[20:23], v143, s[80:81]
	ds_bpermute_b32 v142, v255, v134
	ds_bpermute_b32 v143, v153, v134
	s_waitcnt lgkmcnt(0)
	v_and_or_b32 v142, v142, s90, v240
	v_and_or_b32 v143, v143, s90, v240
	global_load_dwordx4 v[24:27], v142, s[80:81]
	global_load_dwordx4 v[28:31], v143, s[80:81]
	ds_bpermute_b32 v142, v249, v135
	ds_bpermute_b32 v143, v250, v135
	s_waitcnt lgkmcnt(0)
	v_and_or_b32 v142, v142, s90, v240
	v_and_or_b32 v143, v143, s90, v240
	global_load_dwordx4 v[32:35], v142, s[80:81]
	global_load_dwordx4 v[36:39], v143, s[80:81]
	ds_bpermute_b32 v142, v251, v135
	ds_bpermute_b32 v143, v252, v135
	s_waitcnt lgkmcnt(0)
	v_and_or_b32 v142, v142, s90, v240
	v_and_or_b32 v143, v143, s90, v240
	global_load_dwordx4 v[40:43], v142, s[80:81]
	global_load_dwordx4 v[44:47], v143, s[80:81]
	ds_bpermute_b32 v142, v253, v135
	ds_bpermute_b32 v143, v254, v135
	s_waitcnt lgkmcnt(0)
	v_and_or_b32 v142, v142, s90, v240
	v_and_or_b32 v143, v143, s90, v240
	global_load_dwordx4 v[48:51], v142, s[80:81]
	global_load_dwordx4 v[52:55], v143, s[80:81]
	ds_bpermute_b32 v142, v255, v135
	ds_bpermute_b32 v143, v153, v135
	s_waitcnt lgkmcnt(0)
	v_and_or_b32 v142, v142, s90, v240
	v_and_or_b32 v143, v143, s90, v240
	global_load_dwordx4 v[56:59], v142, s[80:81]
	global_load_dwordx4 v[60:63], v143, s[80:81]
	s_mov_b32 s92, 1
	s_lshl_b32 vcc_lo, s92, 9
	s_add_u32 vcc_lo, vcc_lo, s101
	v_add_u32_e32 v116, vcc_lo, v234
	ds_read_b32 v134, v116
	ds_read_b32 v135, v116 offset:256

.Lpg0_act:
	v_readlane_b32 s82, v231, 28
	v_readlane_b32 s83, v231, 29
	s_nop 4
	s_lshl_b32 s98, s2, 11
	s_add_u32 s98, s98, s101
	v_add_u32_e32 v116, s98, v234
	v_add_u32_e32 v117, 0x10000, v116
	ds_read_b32 v0, v116 offset:0
	ds_read_b32 v8, v117 offset:0
	ds_read_b32 v1, v116 offset:256
	ds_read_b32 v9, v117 offset:256
	ds_read_b32 v2, v116 offset:512
	ds_read_b32 v10, v117 offset:512
	ds_read_b32 v3, v116 offset:768
	ds_read_b32 v11, v117 offset:768
	ds_read_b32 v4, v116 offset:1024
	ds_read_b32 v12, v117 offset:1024
	ds_read_b32 v5, v116 offset:1280
	ds_read_b32 v13, v117 offset:1280
	ds_read_b32 v6, v116 offset:1536
	ds_read_b32 v14, v117 offset:1536
	ds_read_b32 v7, v116 offset:1792
	ds_read_b32 v15, v117 offset:1792
	s_waitcnt lgkmcnt(0)
	s_lshl_b32 s99, s2, 2
	s_add_u32 s99, s99, s33
	s_add_u32 s99, s99, 0
	s_lshl_b32 s99, s99, 9
	v_and_b32_e32 v0, 0x7f, v0
	v_lshl_add_u32 v0, v0, 2, s99
	global_load_dword v16, v0, s[82:83]
	v_and_b32_e32 v1, 0x7f, v1
	v_lshl_add_u32 v1, v1, 2, s99
	global_load_dword v17, v1, s[82:83]
	s_lshl_b32 s99, s2, 2
	s_add_u32 s99, s99, s33
	s_add_u32 s99, s99, 1
	s_lshl_b32 s99, s99, 9
	v_and_b32_e32 v2, 0x7f, v2
	v_lshl_add_u32 v2, v2, 2, s99
	global_load_dword v18, v2, s[82:83]
	v_and_b32_e32 v3, 0x7f, v3
	v_lshl_add_u32 v3, v3, 2, s99
	global_load_dword v19, v3, s[82:83]
	s_lshl_b32 s99, s2, 2
	s_add_u32 s99, s99, s33
	s_add_u32 s99, s99, 2
	s_lshl_b32 s99, s99, 9
	v_and_b32_e32 v4, 0x7f, v4
	v_lshl_add_u32 v4, v4, 2, s99
	global_load_dword v20, v4, s[82:83]
	v_and_b32_e32 v5, 0x7f, v5
	v_lshl_add_u32 v5, v5, 2, s99
	global_load_dword v21, v5, s[82:83]
	s_lshl_b32 s99, s2, 2
	s_add_u32 s99, s99, s33
	s_add_u32 s99, s99, 3
	s_lshl_b32 s99, s99, 9
	v_and_b32_e32 v6, 0x7f, v6
	v_lshl_add_u32 v6, v6, 2, s99
	global_load_dword v22, v6, s[82:83]
	v_and_b32_e32 v7, 0x7f, v7
	v_lshl_add_u32 v7, v7, 2, s99
	global_load_dword v23, v7, s[82:83]
	v_mul_f32_e32 v8, 0x3c800000, v8
	v_mul_f32_e32 v9, 0x3c800000, v9
	v_mul_f32_e32 v10, 0x3c800000, v10
	v_mul_f32_e32 v11, 0x3c800000, v11
	v_mul_f32_e32 v12, 0x3c800000, v12
	v_mul_f32_e32 v13, 0x3c800000, v13
	v_mul_f32_e32 v14, 0x3c800000, v14
	v_mul_f32_e32 v15, 0x3c800000, v15
	v_mul_f32_e32 v24, 0x3d372713, v8
	v_mul_f32_e32 v25, 0x3d372713, v9
	v_mul_f32_e32 v26, 0x3d372713, v10
	v_mul_f32_e32 v27, 0x3d372713, v11
	v_mul_f32_e32 v28, 0x3d372713, v12
	v_mul_f32_e32 v29, 0x3d372713, v13
	v_mul_f32_e32 v30, 0x3d372713, v14
	v_mul_f32_e32 v31, 0x3d372713, v15
	v_mul_f32_e32 v24, v8, v24
	v_mul_f32_e32 v25, v9, v25
	v_mul_f32_e32 v26, v10, v26
	v_mul_f32_e32 v27, v11, v27
	v_mul_f32_e32 v28, v12, v28
	v_mul_f32_e32 v29, v13, v29
	v_mul_f32_e32 v30, v14, v30
	v_mul_f32_e32 v31, v15, v31
	v_fma_f32 v24, v8, v24, v8
	v_fma_f32 v25, v9, v25, v9
	v_fma_f32 v26, v10, v26, v10
	v_fma_f32 v27, v11, v27, v11
	v_fma_f32 v28, v12, v28, v12
	v_fma_f32 v29, v13, v29, v13
	v_fma_f32 v30, v14, v30, v14
	v_fma_f32 v31, v15, v31, v15
	v_mul_f32_e32 v24, 0xbfcc422a, v24
	v_mul_f32_e32 v25, 0xbfcc422a, v25
	v_mul_f32_e32 v26, 0xbfcc422a, v26
	v_mul_f32_e32 v27, 0xbfcc422a, v27
	v_mul_f32_e32 v28, 0xbfcc422a, v28
	v_mul_f32_e32 v29, 0xbfcc422a, v29
	v_mul_f32_e32 v30, 0xbfcc422a, v30
	v_mul_f32_e32 v31, 0xbfcc422a, v31
	v_mul_f32_e32 v24, 0x3fb8aa3b, v24
	v_mul_f32_e32 v25, 0x3fb8aa3b, v25
	v_mul_f32_e32 v26, 0x3fb8aa3b, v26
	v_mul_f32_e32 v27, 0x3fb8aa3b, v27
	v_mul_f32_e32 v28, 0x3fb8aa3b, v28
	v_mul_f32_e32 v29, 0x3fb8aa3b, v29
	v_mul_f32_e32 v30, 0x3fb8aa3b, v30
	v_mul_f32_e32 v31, 0x3fb8aa3b, v31
	v_exp_f32_e32 v24, v24
	v_exp_f32_e32 v25, v25
	v_exp_f32_e32 v26, v26
	v_exp_f32_e32 v27, v27
	v_exp_f32_e32 v28, v28
	v_exp_f32_e32 v29, v29
	v_exp_f32_e32 v30, v30
	v_exp_f32_e32 v31, v31
	s_nop 0
	v_add_f32_e32 v24, 1.0, v24
	v_add_f32_e32 v25, 1.0, v25
	v_add_f32_e32 v26, 1.0, v26
	v_add_f32_e32 v27, 1.0, v27
	v_add_f32_e32 v28, 1.0, v28
	v_add_f32_e32 v29, 1.0, v29
	v_add_f32_e32 v30, 1.0, v30
	v_add_f32_e32 v31, 1.0, v31
	v_rcp_f32_e32 v24, v24
	v_rcp_f32_e32 v25, v25
	v_rcp_f32_e32 v26, v26
	v_rcp_f32_e32 v27, v27
	v_rcp_f32_e32 v28, v28
	v_rcp_f32_e32 v29, v29
	v_rcp_f32_e32 v30, v30
	v_rcp_f32_e32 v31, v31
	s_nop 0
	v_mul_f32_e32 v24, v8, v24
	v_mul_f32_e32 v25, v9, v25
	v_mul_f32_e32 v26, v10, v26
	v_mul_f32_e32 v27, v11, v27
	v_mul_f32_e32 v28, v12, v28
	v_mul_f32_e32 v29, v13, v29
	v_mul_f32_e32 v30, v14, v30
	v_mul_f32_e32 v31, v15, v31
	s_waitcnt vmcnt(0)
	v_mul_f32_e32 v24, v24, v16
	ds_write_b32 v117, v24 offset:0
	v_mul_f32_e32 v25, v25, v17
	ds_write_b32 v117, v25 offset:256
	v_mul_f32_e32 v26, v26, v18
	ds_write_b32 v117, v26 offset:512
	v_mul_f32_e32 v27, v27, v19
	ds_write_b32 v117, v27 offset:768
	v_mul_f32_e32 v28, v28, v20
	ds_write_b32 v117, v28 offset:1024
	v_mul_f32_e32 v29, v29, v21
	ds_write_b32 v117, v29 offset:1280
	v_mul_f32_e32 v30, v30, v22
	ds_write_b32 v117, v30 offset:1536
	v_mul_f32_e32 v31, v31, v23
	ds_write_b32 v117, v31 offset:1792
	s_add_u32 s2, s2, 1
	s_cmp_lt_u32 s2, 4
	s_cbranch_scc1 .Lpg0_act
; #define PG_ISSUE(BUF, TAB, e0_) do { const int isrc_ = ((e0_) < 64) ? myi0 : myi1; \
;       _Pragma("unroll") for (int e = 0; e < 8; ++e) { const int idx_ = __builtin_amdgcn_readlane(isrc_, ((e0_) + e) & 63); \
;         BUF[e] = *(const u32x4*)((TAB) + (size_t)idx_ * 1024 + lane * 16); } } while (0)
; DEV void peer_gather(const Params& P, int l, int m0, const int* idxs, const float* gs) {
;     ...
; #pragma nounroll
;     for (int e0 = 0; e0 < 128; e0 += 16) {
;       PG_ISSUE(b1, V, e0 + 8);
;       if (e0 == 64 && i + 1 < 16) sort_lists(lane, ni0, ni1, ng0, ng1);
;       PG_V16(b0, e0);
;       if (e0 + 16 < 128) PG_ISSUE(b0, V, e0 + 16);
;       PG_V16(b1, e0 + 8);
	s_waitcnt lgkmcnt(0)
	v_readfirstlane_b32 s80, v126
	v_readfirstlane_b32 s81, v127
	s_nop 4
	s_mov_b32 s90, 0xfffffc00
	s_mov_b32 s100, 0
	s_mov_b32 s98, 0
	s_mov_b32 s99, 0
	s_lshl_b32 vcc_lo, s98, 9
	s_add_u32 vcc_lo, vcc_lo, s101
	v_add_u32_e32 v116, vcc_lo, v234
	ds_read_b32 v134, v116
	ds_read_b32 v135, v116 offset:256
	s_lshl_b32 vcc_lo, s99, 7
	v_add_u32_e32 v240, vcc_lo, v235
	s_waitcnt lgkmcnt(0)
	ds_bpermute_b32 v142, v249, v134
	ds_bpermute_b32 v143, v250, v134
	s_waitcnt lgkmcnt(0)
	v_and_or_b32 v142, v142, s90, v240
	v_and_or_b32 v143, v143, s90, v240
	global_load_dwordx4 v[0:3], v142, s[80:81]
	global_load_dwordx4 v[4:7], v143, s[80:81]
	ds_bpermute_b32 v142, v251, v134
	ds_bpermute_b32 v143, v252, v134
	s_waitcnt lgkmcnt(0)
	v_and_or_b32 v142, v142, s90, v240
	v_and_or_b32 v143, v143, s90, v240
	global_load_dwordx4 v[8:11], v142, s[80:81]
	global_load_dwordx4 v[12:15], v143, s[80:81]
	ds_bpermute_b32 v142, v253, v134
	ds_bpermute_b32 v143, v254, v134
	s_waitcnt lgkmcnt(0)
	v_and_or_b32 v142, v142, s90, v240
	v_and_or_b32 v143, v143, s90, v240
	global_load_dwordx4 v[16:19], v142, s[80:81]
	global_load_dwordx4 v[20:23], v143, s[80:81]
	ds_bpermute_b32 v142, v255, v134
	ds_bpermute_b32 v143, v153, v134
	s_waitcnt lgkmcnt(0)
	v_and_or_b32 v142, v142, s90, v240
	v_and_or_b32 v143, v143, s90, v240
	global_load_dwordx4 v[24:27], v142, s[80:81]
	global_load_dwordx4 v[28:31], v143, s[80:81]
	ds_bpermute_b32 v142, v249, v135
	ds_bpermute_b32 v143, v250, v135
	s_waitcnt lgkmcnt(0)
	v_and_or_b32 v142, v142, s90, v240
	v_and_or_b32 v143, v143, s90, v240
	global_load_dwordx4 v[32:35], v142, s[80:81]
	global_load_dwordx4 v[36:39], v143, s[80:81]
	ds_bpermute_b32 v142, v251, v135
	ds_bpermute_b32 v143, v252, v135
	s_waitcnt lgkmcnt(0)
	v_and_or_b32 v142, v142, s90, v240
	v_and_or_b32 v143, v143, s90, v240
	global_load_dwordx4 v[40:43], v142, s[80:81]
	global_load_dwordx4 v[44:47], v143, s[80:81]
	ds_bpermute_b32 v142, v253, v135
	ds_bpermute_b32 v143, v254, v135
	s_waitcnt lgkmcnt(0)
	v_and_or_b32 v142, v142, s90, v240
	v_and_or_b32 v143, v143, s90, v240
	global_load_dwordx4 v[48:51], v142, s[80:81]
	global_load_dwordx4 v[52:55], v143, s[80:81]
	ds_bpermute_b32 v142, v255, v135
	ds_bpermute_b32 v143, v153, v135
	s_waitcnt lgkmcnt(0)
	v_and_or_b32 v142, v142, s90, v240
	v_and_or_b32 v143, v143, s90, v240
	global_load_dwordx4 v[56:59], v142, s[80:81]
	global_load_dwordx4 v[60:63], v143, s[80:81]
	s_mov_b32 s92, 1
	s_lshl_b32 vcc_lo, s92, 9
	s_add_u32 vcc_lo, vcc_lo, s101
	v_add_u32_e32 v116, vcc_lo, v234
	ds_read_b32 v134, v116
	ds_read_b32 v135, v116 offset:256
	s_lshl_b32 vcc_lo, s98, 9
	s_add_u32 vcc_lo, vcc_lo, s101
	s_add_u32 vcc_lo, vcc_lo, 0x10000
	v_add_u32_e32 v117, vcc_lo, v234
	ds_read_b32 v136, v117
	ds_read_b32 v137, v117 offset:256
	s_waitcnt vmcnt(0)

; DEV void sort_lists(int lane, int& myi0, int& myi1, float& myg0, float& myg1) {
; #pragma unroll
;     for (int k = 2; k <= 128; k <<= 1) {
; #pragma unroll
;       for (int j = k >> 1; j >= 1; j >>= 1) {
;         if (j == 64) {
;           const bool sw_ = myi1 < myi0;
;           const int ti = sw_ ? myi1 : myi0, tj = sw_ ? myi0 : myi1; const float tg = sw_ ? myg1 : myg0, th = sw_ ? myg0 : myg1;
;           myi0 = ti; myi1 = tj; myg0 = tg; myg1 = th;
;         } else {
;           const bool lower = (lane & j) == 0;
;           {
;             const bool up = (k == 128) ? true : ((k == 64) ? true : ((lane & k) == 0));
;             const int oi = __shfl_xor(myi0, j); const float og = __shfl_xor(myg0, j);
;             const bool take = (lower == up) ? (oi < myi0) : (oi > myi0);
;             myi0 = take ? oi : myi0; myg0 = take ? og : myg0;
;           }
;           {
;             const bool up = (k == 128) ? true : ((k == 64) ? false : ((lane & k) == 0));
;             const int oi = __shfl_xor(myi1, j); const float og = __shfl_xor(myg1, j);
;             const bool take = (lower == up) ? (oi < myi1) : (oi > myi1);
;             myi1 = take ? oi : myi1; myg1 = take ? og : myg1;
;           }
;         }
;       }
;     }
; }
; DEV void peer_gather(const Params& P, int l, int m0, const int* idxs, const float* gs) {
;     ...
;   int ni0 = idxs[(wid * 16) * 128 + lane], ni1 = idxs[(wid * 16) * 128 + 64 + lane];
;   float ng0 = gs[(wid * 16) * 128 + lane], ng1 = gs[(wid * 16) * 128 + 64 + lane];
.Lpg1_p0:
	v_readlane_b32 s82, v231, 13
	v_readlane_b32 s83, v231, 14
	s_nop 4
	s_lshl_b32 s98, s2, 2
	s_add_u32 s98, s98, s33
	s_add_u32 s98, s98, 0
	s_lshl_b32 s98, s98, 9
	v_add_u32_e32 v116, s98, v234
	global_load_dword v241, v116, s[82:83]
	global_load_dword v242, v116, s[82:83] offset:256
	s_lshl_b32 s98, s2, 2
	s_add_u32 s98, s98, s33
	s_add_u32 s98, s98, 1
	s_lshl_b32 s98, s98, 9
	v_add_u32_e32 v117, s98, v234
	global_load_dword v243, v117, s[82:83]
	global_load_dword v244, v117, s[82:83] offset:256
	s_lshl_b32 s98, s2, 2
	s_add_u32 s98, s98, s33
	s_add_u32 s98, s98, 2
	s_lshl_b32 s98, s98, 9
	v_add_u32_e32 v118, s98, v234
	global_load_dword v245, v118, s[82:83]
	global_load_dword v246, v118, s[82:83] offset:256
	s_lshl_b32 s98, s2, 2
	s_add_u32 s98, s98, s33
	s_add_u32 s98, s98, 3
	s_lshl_b32 s98, s98, 9
	v_add_u32_e32 v119, s98, v234
	global_load_dword v247, v119, s[82:83]
	global_load_dword v248, v119, s[82:83] offset:256
	s_waitcnt vmcnt(0)
	v_or_b32_e32 v116, 64, v233
	v_lshl_or_b32 v241, v241, 7, v233
	v_lshl_or_b32 v242, v242, 7, v116
	v_lshl_or_b32 v243, v243, 7, v233
	v_lshl_or_b32 v244, v244, 7, v116
	v_lshl_or_b32 v245, v245, 7, v233
	v_lshl_or_b32 v246, v246, 7, v116
	v_lshl_or_b32 v247, v247, 7, v233
	v_lshl_or_b32 v248, v248, 7, v116
	v_xor_b32_e32 v116, 4, v234
	ds_bpermute_b32 v0, v116, v241
	ds_bpermute_b32 v1, v116, v243
	ds_bpermute_b32 v2, v116, v245
	ds_bpermute_b32 v3, v116, v247
	ds_bpermute_b32 v4, v116, v242
	ds_bpermute_b32 v5, v116, v244
	ds_bpermute_b32 v6, v116, v246
	ds_bpermute_b32 v7, v116, v248
	s_waitcnt lgkmcnt(0)
	s_mov_b32 s88, 0x99999999
	s_mov_b32 s89, 0x99999999
	v_min_u32_e32 v104, v241, v0
	v_max_u32_e32 v105, v241, v0
	v_cndmask_b32_e64 v241, v105, v104, s[88:89]
	v_min_u32_e32 v106, v243, v1
	v_max_u32_e32 v107, v243, v1
	v_cndmask_b32_e64 v243, v107, v106, s[88:89]
	v_min_u32_e32 v104, v245, v2
	v_max_u32_e32 v105, v245, v2
	v_cndmask_b32_e64 v245, v105, v104, s[88:89]
	v_min_u32_e32 v106, v247, v3
	v_max_u32_e32 v107, v247, v3
	v_cndmask_b32_e64 v247, v107, v106, s[88:89]
	v_min_u32_e32 v104, v242, v4
	v_max_u32_e32 v105, v242, v4
	v_cndmask_b32_e64 v242, v105, v104, s[88:89]
	v_min_u32_e32 v106, v244, v5
	v_max_u32_e32 v107, v244, v5
	v_cndmask_b32_e64 v244, v107, v106, s[88:89]
	v_min_u32_e32 v104, v246, v6
	v_max_u32_e32 v105, v246, v6
	v_cndmask_b32_e64 v246, v105, v104, s[88:89]
	v_min_u32_e32 v106, v248, v7
	v_max_u32_e32 v107, v248, v7
	v_cndmask_b32_e64 v248, v107, v106, s[88:89]
	v_xor_b32_e32 v116, 8, v234
	ds_bpermute_b32 v0, v116, v241
	ds_bpermute_b32 v1, v116, v243
	ds_bpermute_b32 v2, v116, v245
	ds_bpermute_b32 v3, v116, v247
	ds_bpermute_b32 v4, v116, v242
	ds_bpermute_b32 v5, v116, v244
	ds_bpermute_b32 v6, v116, v246
	ds_bpermute_b32 v7, v116, v248
	s_waitcnt lgkmcnt(0)
	s_mov_b32 s88, 0xc3c3c3c3
	s_mov_b32 s89, 0xc3c3c3c3
	v_min_u32_e32 v104, v241, v0
	v_max_u32_e32 v105, v241, v0
	v_cndmask_b32_e64 v241, v105, v104, s[88:89]
	v_min_u32_e32 v106, v243, v1
	v_max_u32_e32 v107, v243, v1
	v_cndmask_b32_e64 v243, v107, v106, s[88:89]
	v_min_u32_e32 v104, v245, v2
	v_max_u32_e32 v105, v245, v2
	v_cndmask_b32_e64 v245, v105, v104, s[88:89]
	v_min_u32_e32 v106, v247, v3
	v_max_u32_e32 v107, v247, v3
	v_cndmask_b32_e64 v247, v107, v106, s[88:89]
	v_min_u32_e32 v104, v242, v4
	v_max_u32_e32 v105, v242, v4
	v_cndmask_b32_e64 v242, v105, v104, s[88:89]
	v_min_u32_e32 v106, v244, v5
	v_max_u32_e32 v107, v244, v5
	v_cndmask_b32_e64 v244, v107, v106, s[88:89]
	v_min_u32_e32 v104, v246, v6
	v_max_u32_e32 v105, v246, v6
	v_cndmask_b32_e64 v246, v105, v104, s[88:89]
	v_min_u32_e32 v106, v248, v7
	v_max_u32_e32 v107, v248, v7
	v_cndmask_b32_e64 v248, v107, v106, s[88:89]
	v_xor_b32_e32 v116, 4, v234
	ds_bpermute_b32 v0, v116, v241
	ds_bpermute_b32 v1, v116, v243
	ds_bpermute_b32 v2, v116, v245
	ds_bpermute_b32 v3, v116, v247
	ds_bpermute_b32 v4, v116, v242
	ds_bpermute_b32 v5, v116, v244
	ds_bpermute_b32 v6, v116, v246
	ds_bpermute_b32 v7, v116, v248
	s_waitcnt lgkmcnt(0)
	s_mov_b32 s88, 0xa5a5a5a5
	s_mov_b32 s89, 0xa5a5a5a5
	v_min_u32_e32 v104, v241, v0
	v_max_u32_e32 v105, v241, v0
	v_cndmask_b32_e64 v241, v105, v104, s[88:89]
	v_min_u32_e32 v106, v243, v1
	v_max_u32_e32 v107, v243, v1
	v_cndmask_b32_e64 v243, v107, v106, s[88:89]
	v_min_u32_e32 v104, v245, v2
	v_max_u32_e32 v105, v245, v2
	v_cndmask_b32_e64 v245, v105, v104, s[88:89]
	v_min_u32_e32 v106, v247, v3
	v_max_u32_e32 v107, v247, v3
	v_cndmask_b32_e64 v247, v107, v106, s[88:89]
	v_min_u32_e32 v104, v242, v4
	v_max_u32_e32 v105, v242, v4
	v_cndmask_b32_e64 v242, v105, v104, s[88:89]
	v_min_u32_e32 v106, v244, v5
	v_max_u32_e32 v107, v244, v5
	v_cndmask_b32_e64 v244, v107, v106, s[88:89]
	v_min_u32_e32 v104, v246, v6
	v_max_u32_e32 v105, v246, v6
	v_cndmask_b32_e64 v246, v105, v104, s[88:89]
	v_min_u32_e32 v106, v248, v7
	v_max_u32_e32 v107, v248, v7
	v_cndmask_b32_e64 v248, v107, v106, s[88:89]
	v_xor_b32_e32 v116, 16, v234
	ds_bpermute_b32 v0, v116, v241
	ds_bpermute_b32 v1, v116, v243
	ds_bpermute_b32 v2, v116, v245
	ds_bpermute_b32 v3, v116, v247
	ds_bpermute_b32 v4, v116, v242
	ds_bpermute_b32 v5, v116, v244
	ds_bpermute_b32 v6, v116, v246
	ds_bpermute_b32 v7, v116, v248
	s_waitcnt lgkmcnt(0)
; DEV void sort_lists(int lane, int& myi0, int& myi1, float& myg0, float& myg1) {
; #pragma unroll
;     for (int k = 2; k <= 128; k <<= 1) {
; #pragma unroll
;       for (int j = k >> 1; j >= 1; j >>= 1) {
;         if (j == 64) {
;           const bool sw_ = myi1 < myi0;
;           const int ti = sw_ ? myi1 : myi0, tj = sw_ ? myi0 : myi1; const float tg = sw_ ? myg1 : myg0, th = sw_ ? myg0 : myg1;
;           myi0 = ti; myi1 = tj; myg0 = tg; myg1 = th;
;         } else {
;           const bool lower = (lane & j) == 0;
;           {
;             const bool up = (k == 128) ? true : ((k == 64) ? true : ((lane & k) == 0));
;             const int oi = __shfl_xor(myi0, j); const float og = __shfl_xor(myg0, j);
;             const bool take = (lower == up) ? (oi < myi0) : (oi > myi0);
;             myi0 = take ? oi : myi0; myg0 = take ? og : myg0;
;           }
;           {
;             const bool up = (k == 128) ? true : ((k == 64) ? false : ((lane & k) == 0));
;             const int oi = __shfl_xor(myi1, j); const float og = __shfl_xor(myg1, j);
;             const bool take = (lower == up) ? (oi < myi1) : (oi > myi1);
;             myi1 = take ? oi : myi1; myg1 = take ? og : myg1;
;           }
;         }
;       }
;     }
; }
	s_mov_b32 s88, 0xf00ff00f
	s_mov_b32 s89, 0xf00ff00f
	v_min_u32_e32 v104, v241, v0
	v_max_u32_e32 v105, v241, v0
	v_cndmask_b32_e64 v241, v105, v104, s[88:89]
	v_min_u32_e32 v106, v243, v1
	v_max_u32_e32 v107, v243, v1
	v_cndmask_b32_e64 v243, v107, v106, s[88:89]
	v_min_u32_e32 v104, v245, v2
	v_max_u32_e32 v105, v245, v2
	v_cndmask_b32_e64 v245, v105, v104, s[88:89]
	v_min_u32_e32 v106, v247, v3
	v_max_u32_e32 v107, v247, v3
	v_cndmask_b32_e64 v247, v107, v106, s[88:89]
	v_min_u32_e32 v104, v242, v4
	v_max_u32_e32 v105, v242, v4
	v_cndmask_b32_e64 v242, v105, v104, s[88:89]
	v_min_u32_e32 v106, v244, v5
	v_max_u32_e32 v107, v244, v5
	v_cndmask_b32_e64 v244, v107, v106, s[88:89]
	v_min_u32_e32 v104, v246, v6
	v_max_u32_e32 v105, v246, v6
	v_cndmask_b32_e64 v246, v105, v104, s[88:89]
	v_min_u32_e32 v106, v248, v7
	v_max_u32_e32 v107, v248, v7
	v_cndmask_b32_e64 v248, v107, v106, s[88:89]
	v_xor_b32_e32 v116, 8, v234
	ds_bpermute_b32 v0, v116, v241
	ds_bpermute_b32 v1, v116, v243
	ds_bpermute_b32 v2, v116, v245
	ds_bpermute_b32 v3, v116, v247
	ds_bpermute_b32 v4, v116, v242
	ds_bpermute_b32 v5, v116, v244
	ds_bpermute_b32 v6, v116, v246
	ds_bpermute_b32 v7, v116, v248
	s_waitcnt lgkmcnt(0)
	s_mov_b32 s88, 0xcc33cc33
	s_mov_b32 s89, 0xcc33cc33
	v_min_u32_e32 v104, v241, v0
	v_max_u32_e32 v105, v241, v0
	v_cndmask_b32_e64 v241, v105, v104, s[88:89]
	v_min_u32_e32 v106, v243, v1
	v_max_u32_e32 v107, v243, v1
	v_cndmask_b32_e64 v243, v107, v106, s[88:89]
	v_min_u32_e32 v104, v245, v2
	v_max_u32_e32 v105, v245, v2
	v_cndmask_b32_e64 v245, v105, v104, s[88:89]
	v_min_u32_e32 v106, v247, v3
	v_max_u32_e32 v107, v247, v3
	v_cndmask_b32_e64 v247, v107, v106, s[88:89]
	v_min_u32_e32 v104, v242, v4
	v_max_u32_e32 v105, v242, v4
	v_cndmask_b32_e64 v242, v105, v104, s[88:89]
	v_min_u32_e32 v106, v244, v5
	v_max_u32_e32 v107, v244, v5
	v_cndmask_b32_e64 v244, v107, v106, s[88:89]
	v_min_u32_e32 v104, v246, v6
	v_max_u32_e32 v105, v246, v6
	v_cndmask_b32_e64 v246, v105, v104, s[88:89]
	v_min_u32_e32 v106, v248, v7
	v_max_u32_e32 v107, v248, v7
	v_cndmask_b32_e64 v248, v107, v106, s[88:89]
	v_xor_b32_e32 v116, 4, v234
	ds_bpermute_b32 v0, v116, v241
	ds_bpermute_b32 v1, v116, v243
	ds_bpermute_b32 v2, v116, v245
	ds_bpermute_b32 v3, v116, v247
	ds_bpermute_b32 v4, v116, v242
	ds_bpermute_b32 v5, v116, v244
	ds_bpermute_b32 v6, v116, v246
	ds_bpermute_b32 v7, v116, v248
	s_waitcnt lgkmcnt(0)
	s_mov_b32 s88, 0xaa55aa55
	s_mov_b32 s89, 0xaa55aa55
	v_min_u32_e32 v104, v241, v0
	v_max_u32_e32 v105, v241, v0
	v_cndmask_b32_e64 v241, v105, v104, s[88:89]
	v_min_u32_e32 v106, v243, v1
	v_max_u32_e32 v107, v243, v1
	v_cndmask_b32_e64 v243, v107, v106, s[88:89]
	v_min_u32_e32 v104, v245, v2
	v_max_u32_e32 v105, v245, v2
	v_cndmask_b32_e64 v245, v105, v104, s[88:89]
	v_min_u32_e32 v106, v247, v3
	v_max_u32_e32 v107, v247, v3
	v_cndmask_b32_e64 v247, v107, v106, s[88:89]
	v_min_u32_e32 v104, v242, v4
	v_max_u32_e32 v105, v242, v4
	v_cndmask_b32_e64 v242, v105, v104, s[88:89]
	v_min_u32_e32 v106, v244, v5
	v_max_u32_e32 v107, v244, v5
	v_cndmask_b32_e64 v244, v107, v106, s[88:89]
	v_min_u32_e32 v104, v246, v6
	v_max_u32_e32 v105, v246, v6
	v_cndmask_b32_e64 v246, v105, v104, s[88:89]
	v_min_u32_e32 v106, v248, v7
	v_max_u32_e32 v107, v248, v7
	v_cndmask_b32_e64 v248, v107, v106, s[88:89]
	v_xor_b32_e32 v116, 32, v234
	ds_bpermute_b32 v0, v116, v241
	ds_bpermute_b32 v1, v116, v243
	ds_bpermute_b32 v2, v116, v245
	ds_bpermute_b32 v3, v116, v247
	ds_bpermute_b32 v4, v116, v242
	ds_bpermute_b32 v5, v116, v244
	ds_bpermute_b32 v6, v116, v246
	ds_bpermute_b32 v7, v116, v248
	s_waitcnt lgkmcnt(0)
	s_mov_b32 s88, 0xff0000ff
	s_mov_b32 s89, 0xff0000ff
	v_min_u32_e32 v104, v241, v0
	v_max_u32_e32 v105, v241, v0
	v_cndmask_b32_e64 v241, v105, v104, s[88:89]
	v_min_u32_e32 v106, v243, v1
	v_max_u32_e32 v107, v243, v1
	v_cndmask_b32_e64 v243, v107, v106, s[88:89]
	v_min_u32_e32 v104, v245, v2
	v_max_u32_e32 v105, v245, v2
	v_cndmask_b32_e64 v245, v105, v104, s[88:89]
	v_min_u32_e32 v106, v247, v3
	v_max_u32_e32 v107, v247, v3
	v_cndmask_b32_e64 v247, v107, v106, s[88:89]
	v_min_u32_e32 v104, v242, v4
	v_max_u32_e32 v105, v242, v4
	v_cndmask_b32_e64 v242, v105, v104, s[88:89]
	v_min_u32_e32 v106, v244, v5
	v_max_u32_e32 v107, v244, v5
	v_cndmask_b32_e64 v244, v107, v106, s[88:89]
	v_min_u32_e32 v104, v246, v6
	v_max_u32_e32 v105, v246, v6
	v_cndmask_b32_e64 v246, v105, v104, s[88:89]
	v_min_u32_e32 v106, v248, v7
	v_max_u32_e32 v107, v248, v7
	v_cndmask_b32_e64 v248, v107, v106, s[88:89]
	v_xor_b32_e32 v116, 16, v234
	ds_bpermute_b32 v0, v116, v241
	ds_bpermute_b32 v1, v116, v243
	ds_bpermute_b32 v2, v116, v245
	ds_bpermute_b32 v3, v116, v247
	ds_bpermute_b32 v4, v116, v242
	ds_bpermute_b32 v5, v116, v244
	ds_bpermute_b32 v6, v116, v246
	ds_bpermute_b32 v7, v116, v248
	s_waitcnt lgkmcnt(0)
	s_mov_b32 s88, 0xf0f00f0f
	s_mov_b32 s89, 0xf0f00f0f
	v_min_u32_e32 v104, v241, v0
	v_max_u32_e32 v105, v241, v0
	v_cndmask_b32_e64 v241, v105, v104, s[88:89]
	v_min_u32_e32 v106, v243, v1
	v_max_u32_e32 v107, v243, v1
	v_cndmask_b32_e64 v243, v107, v106, s[88:89]
	v_min_u32_e32 v104, v245, v2
	v_max_u32_e32 v105, v245, v2
	v_cndmask_b32_e64 v245, v105, v104, s[88:89]
	v_min_u32_e32 v106, v247, v3
	v_max_u32_e32 v107, v247, v3
	v_cndmask_b32_e64 v247, v107, v106, s[88:89]
	v_min_u32_e32 v104, v242, v4
	v_max_u32_e32 v105, v242, v4
	v_cndmask_b32_e64 v242, v105, v104, s[88:89]
	v_min_u32_e32 v106, v244, v5
	v_max_u32_e32 v107, v244, v5
	v_cndmask_b32_e64 v244, v107, v106, s[88:89]
	v_min_u32_e32 v104, v246, v6
	v_max_u32_e32 v105, v246, v6
	v_cndmask_b32_e64 v246, v105, v104, s[88:89]
	v_min_u32_e32 v106, v248, v7
	v_max_u32_e32 v107, v248, v7
	v_cndmask_b32_e64 v248, v107, v106, s[88:89]
	v_xor_b32_e32 v116, 8, v234
	ds_bpermute_b32 v0, v116, v241
	ds_bpermute_b32 v1, v116, v243
	ds_bpermute_b32 v2, v116, v245
	ds_bpermute_b32 v3, v116, v247
	ds_bpermute_b32 v4, v116, v242
	ds_bpermute_b32 v5, v116, v244
	ds_bpermute_b32 v6, v116, v246
	ds_bpermute_b32 v7, v116, v248
	s_waitcnt lgkmcnt(0)
; DEV void sort_lists(int lane, int& myi0, int& myi1, float& myg0, float& myg1) {
; #pragma unroll
;     for (int k = 2; k <= 128; k <<= 1) {
; #pragma unroll
;       for (int j = k >> 1; j >= 1; j >>= 1) {
;         if (j == 64) {
;           const bool sw_ = myi1 < myi0;
;           const int ti = sw_ ? myi1 : myi0, tj = sw_ ? myi0 : myi1; const float tg = sw_ ? myg1 : myg0, th = sw_ ? myg0 : myg1;
;           myi0 = ti; myi1 = tj; myg0 = tg; myg1 = th;
;         } else {
;           const bool lower = (lane & j) == 0;
;           {
;             const bool up = (k == 128) ? true : ((k == 64) ? true : ((lane & k) == 0));
;             const int oi = __shfl_xor(myi0, j); const float og = __shfl_xor(myg0, j);
;             const bool take = (lower == up) ? (oi < myi0) : (oi > myi0);
;             myi0 = take ? oi : myi0; myg0 = take ? og : myg0;
;           }
;           {
;             const bool up = (k == 128) ? true : ((k == 64) ? false : ((lane & k) == 0));
;             const int oi = __shfl_xor(myi1, j); const float og = __shfl_xor(myg1, j);
;             const bool take = (lower == up) ? (oi < myi1) : (oi > myi1);
;             myi1 = take ? oi : myi1; myg1 = take ? og : myg1;
;           }
;         }
;       }
;     }
; }
	s_mov_b32 s88, 0xcccc3333
	s_mov_b32 s89, 0xcccc3333
	v_min_u32_e32 v104, v241, v0
	v_max_u32_e32 v105, v241, v0
	v_cndmask_b32_e64 v241, v105, v104, s[88:89]
	v_min_u32_e32 v106, v243, v1
	v_max_u32_e32 v107, v243, v1
	v_cndmask_b32_e64 v243, v107, v106, s[88:89]
	v_min_u32_e32 v104, v245, v2
	v_max_u32_e32 v105, v245, v2
	v_cndmask_b32_e64 v245, v105, v104, s[88:89]
	v_min_u32_e32 v106, v247, v3
	v_max_u32_e32 v107, v247, v3
	v_cndmask_b32_e64 v247, v107, v106, s[88:89]
	v_min_u32_e32 v104, v242, v4
	v_max_u32_e32 v105, v242, v4
	v_cndmask_b32_e64 v242, v105, v104, s[88:89]
	v_min_u32_e32 v106, v244, v5
	v_max_u32_e32 v107, v244, v5
	v_cndmask_b32_e64 v244, v107, v106, s[88:89]
	v_min_u32_e32 v104, v246, v6
	v_max_u32_e32 v105, v246, v6
	v_cndmask_b32_e64 v246, v105, v104, s[88:89]
	v_min_u32_e32 v106, v248, v7
	v_max_u32_e32 v107, v248, v7
	v_cndmask_b32_e64 v248, v107, v106, s[88:89]
	v_xor_b32_e32 v116, 4, v234
	ds_bpermute_b32 v0, v116, v241
	ds_bpermute_b32 v1, v116, v243
	ds_bpermute_b32 v2, v116, v245
	ds_bpermute_b32 v3, v116, v247
	ds_bpermute_b32 v4, v116, v242
	ds_bpermute_b32 v5, v116, v244
	ds_bpermute_b32 v6, v116, v246
	ds_bpermute_b32 v7, v116, v248
	s_waitcnt lgkmcnt(0)
	s_mov_b32 s88, 0xaaaa5555
	s_mov_b32 s89, 0xaaaa5555
	v_min_u32_e32 v104, v241, v0
	v_max_u32_e32 v105, v241, v0
	v_cndmask_b32_e64 v241, v105, v104, s[88:89]
	v_min_u32_e32 v106, v243, v1
	v_max_u32_e32 v107, v243, v1
	v_cndmask_b32_e64 v243, v107, v106, s[88:89]
	v_min_u32_e32 v104, v245, v2
	v_max_u32_e32 v105, v245, v2
	v_cndmask_b32_e64 v245, v105, v104, s[88:89]
	v_min_u32_e32 v106, v247, v3
	v_max_u32_e32 v107, v247, v3
	v_cndmask_b32_e64 v247, v107, v106, s[88:89]
	v_min_u32_e32 v104, v242, v4
	v_max_u32_e32 v105, v242, v4
	v_cndmask_b32_e64 v242, v105, v104, s[88:89]
	v_min_u32_e32 v106, v244, v5
	v_max_u32_e32 v107, v244, v5
	v_cndmask_b32_e64 v244, v107, v106, s[88:89]
	v_min_u32_e32 v104, v246, v6
	v_max_u32_e32 v105, v246, v6
	v_cndmask_b32_e64 v246, v105, v104, s[88:89]
	v_min_u32_e32 v106, v248, v7
	v_max_u32_e32 v107, v248, v7
	v_cndmask_b32_e64 v248, v107, v106, s[88:89]
	v_xor_b32_e32 v116, 64, v234
	ds_bpermute_b32 v0, v116, v241
	ds_bpermute_b32 v1, v116, v243
	ds_bpermute_b32 v2, v116, v245
	ds_bpermute_b32 v3, v116, v247
	ds_bpermute_b32 v4, v116, v242
	ds_bpermute_b32 v5, v116, v244
	ds_bpermute_b32 v6, v116, v246
	ds_bpermute_b32 v7, v116, v248
	s_waitcnt lgkmcnt(0)
	s_mov_b32 s88, 0xffff
	s_mov_b32 s89, 0xffff0000
	v_min_u32_e32 v104, v241, v0
	v_max_u32_e32 v105, v241, v0
	v_cndmask_b32_e64 v241, v105, v104, s[88:89]
	v_min_u32_e32 v106, v243, v1
	v_max_u32_e32 v107, v243, v1
	v_cndmask_b32_e64 v243, v107, v106, s[88:89]
	v_min_u32_e32 v104, v245, v2
	v_max_u32_e32 v105, v245, v2
	v_cndmask_b32_e64 v245, v105, v104, s[88:89]
	v_min_u32_e32 v106, v247, v3
	v_max_u32_e32 v107, v247, v3
	v_cndmask_b32_e64 v247, v107, v106, s[88:89]
	v_min_u32_e32 v104, v242, v4
	v_max_u32_e32 v105, v242, v4
	v_cndmask_b32_e64 v242, v105, v104, s[88:89]
	v_min_u32_e32 v106, v244, v5
	v_max_u32_e32 v107, v244, v5
	v_cndmask_b32_e64 v244, v107, v106, s[88:89]
	v_min_u32_e32 v104, v246, v6
	v_max_u32_e32 v105, v246, v6
	v_cndmask_b32_e64 v246, v105, v104, s[88:89]
	v_min_u32_e32 v106, v248, v7
	v_max_u32_e32 v107, v248, v7
	v_cndmask_b32_e64 v248, v107, v106, s[88:89]
	v_xor_b32_e32 v116, 32, v234
	ds_bpermute_b32 v0, v116, v241
	ds_bpermute_b32 v1, v116, v243
	ds_bpermute_b32 v2, v116, v245
	ds_bpermute_b32 v3, v116, v247
	ds_bpermute_b32 v4, v116, v242
	ds_bpermute_b32 v5, v116, v244
	ds_bpermute_b32 v6, v116, v246
	ds_bpermute_b32 v7, v116, v248
	s_waitcnt lgkmcnt(0)
	s_mov_b32 s88, 0xff00ff
	s_mov_b32 s89, 0xff00ff00
	v_min_u32_e32 v104, v241, v0
	v_max_u32_e32 v105, v241, v0
	v_cndmask_b32_e64 v241, v105, v104, s[88:89]
	v_min_u32_e32 v106, v243, v1
	v_max_u32_e32 v107, v243, v1
	v_cndmask_b32_e64 v243, v107, v106, s[88:89]
	v_min_u32_e32 v104, v245, v2
	v_max_u32_e32 v105, v245, v2
	v_cndmask_b32_e64 v245, v105, v104, s[88:89]
	v_min_u32_e32 v106, v247, v3
	v_max_u32_e32 v107, v247, v3
	v_cndmask_b32_e64 v247, v107, v106, s[88:89]
	v_min_u32_e32 v104, v242, v4
	v_max_u32_e32 v105, v242, v4
	v_cndmask_b32_e64 v242, v105, v104, s[88:89]
	v_min_u32_e32 v106, v244, v5
	v_max_u32_e32 v107, v244, v5
	v_cndmask_b32_e64 v244, v107, v106, s[88:89]
	v_min_u32_e32 v104, v246, v6
	v_max_u32_e32 v105, v246, v6
	v_cndmask_b32_e64 v246, v105, v104, s[88:89]
	v_min_u32_e32 v106, v248, v7
	v_max_u32_e32 v107, v248, v7
	v_cndmask_b32_e64 v248, v107, v106, s[88:89]
	v_xor_b32_e32 v116, 16, v234
	ds_bpermute_b32 v0, v116, v241
	ds_bpermute_b32 v1, v116, v243
	ds_bpermute_b32 v2, v116, v245
	ds_bpermute_b32 v3, v116, v247
	ds_bpermute_b32 v4, v116, v242
	ds_bpermute_b32 v5, v116, v244
	ds_bpermute_b32 v6, v116, v246
	ds_bpermute_b32 v7, v116, v248
	s_waitcnt lgkmcnt(0)
	s_mov_b32 s88, 0xf0f0f0f
	s_mov_b32 s89, 0xf0f0f0f0
	v_min_u32_e32 v104, v241, v0
	v_max_u32_e32 v105, v241, v0
	v_cndmask_b32_e64 v241, v105, v104, s[88:89]
	v_min_u32_e32 v106, v243, v1
	v_max_u32_e32 v107, v243, v1
	v_cndmask_b32_e64 v243, v107, v106, s[88:89]
	v_min_u32_e32 v104, v245, v2
	v_max_u32_e32 v105, v245, v2
	v_cndmask_b32_e64 v245, v105, v104, s[88:89]
	v_min_u32_e32 v106, v247, v3
	v_max_u32_e32 v107, v247, v3
	v_cndmask_b32_e64 v247, v107, v106, s[88:89]
	v_min_u32_e32 v104, v242, v4
	v_max_u32_e32 v105, v242, v4
	v_cndmask_b32_e64 v242, v105, v104, s[88:89]
	v_min_u32_e32 v106, v244, v5
	v_max_u32_e32 v107, v244, v5
	v_cndmask_b32_e64 v244, v107, v106, s[88:89]
	v_min_u32_e32 v104, v246, v6
	v_max_u32_e32 v105, v246, v6
	v_cndmask_b32_e64 v246, v105, v104, s[88:89]
	v_min_u32_e32 v106, v248, v7
	v_max_u32_e32 v107, v248, v7
	v_cndmask_b32_e64 v248, v107, v106, s[88:89]
	v_xor_b32_e32 v116, 8, v234
	ds_bpermute_b32 v0, v116, v241
	ds_bpermute_b32 v1, v116, v243
	ds_bpermute_b32 v2, v116, v245
	ds_bpermute_b32 v3, v116, v247
	ds_bpermute_b32 v4, v116, v242
	ds_bpermute_b32 v5, v116, v244
	ds_bpermute_b32 v6, v116, v246
	ds_bpermute_b32 v7, v116, v248
	s_waitcnt lgkmcnt(0)
; DEV void sort_lists(int lane, int& myi0, int& myi1, float& myg0, float& myg1) {
; #pragma unroll
;     for (int k = 2; k <= 128; k <<= 1) {
; #pragma unroll
;       for (int j = k >> 1; j >= 1; j >>= 1) {
;         if (j == 64) {
;           const bool sw_ = myi1 < myi0;
;           const int ti = sw_ ? myi1 : myi0, tj = sw_ ? myi0 : myi1; const float tg = sw_ ? myg1 : myg0, th = sw_ ? myg0 : myg1;
;           myi0 = ti; myi1 = tj; myg0 = tg; myg1 = th;
;         } else {
;           const bool lower = (lane & j) == 0;
;           {
;             const bool up = (k == 128) ? true : ((k == 64) ? true : ((lane & k) == 0));
;             const int oi = __shfl_xor(myi0, j); const float og = __shfl_xor(myg0, j);
;             const bool take = (lower == up) ? (oi < myi0) : (oi > myi0);
;             myi0 = take ? oi : myi0; myg0 = take ? og : myg0;
;           }
;           {
;             const bool up = (k == 128) ? true : ((k == 64) ? false : ((lane & k) == 0));
;             const int oi = __shfl_xor(myi1, j); const float og = __shfl_xor(myg1, j);
;             const bool take = (lower == up) ? (oi < myi1) : (oi > myi1);
;             myi1 = take ? oi : myi1; myg1 = take ? og : myg1;
;           }
;         }
;       }
;     }
; }
	s_mov_b32 s88, 0x33333333
	s_mov_b32 s89, 0xcccccccc
	v_min_u32_e32 v104, v241, v0
	v_max_u32_e32 v105, v241, v0
	v_cndmask_b32_e64 v241, v105, v104, s[88:89]
	v_min_u32_e32 v106, v243, v1
	v_max_u32_e32 v107, v243, v1
	v_cndmask_b32_e64 v243, v107, v106, s[88:89]
	v_min_u32_e32 v104, v245, v2
	v_max_u32_e32 v105, v245, v2
	v_cndmask_b32_e64 v245, v105, v104, s[88:89]
	v_min_u32_e32 v106, v247, v3
	v_max_u32_e32 v107, v247, v3
	v_cndmask_b32_e64 v247, v107, v106, s[88:89]
	v_min_u32_e32 v104, v242, v4
	v_max_u32_e32 v105, v242, v4
	v_cndmask_b32_e64 v242, v105, v104, s[88:89]
	v_min_u32_e32 v106, v244, v5
	v_max_u32_e32 v107, v244, v5
	v_cndmask_b32_e64 v244, v107, v106, s[88:89]
	v_min_u32_e32 v104, v246, v6
	v_max_u32_e32 v105, v246, v6
	v_cndmask_b32_e64 v246, v105, v104, s[88:89]
	v_min_u32_e32 v106, v248, v7
	v_max_u32_e32 v107, v248, v7
	v_cndmask_b32_e64 v248, v107, v106, s[88:89]
	v_xor_b32_e32 v116, 4, v234
	ds_bpermute_b32 v0, v116, v241
	ds_bpermute_b32 v1, v116, v243
	ds_bpermute_b32 v2, v116, v245
	ds_bpermute_b32 v3, v116, v247
	ds_bpermute_b32 v4, v116, v242
	ds_bpermute_b32 v5, v116, v244
	ds_bpermute_b32 v6, v116, v246
	ds_bpermute_b32 v7, v116, v248
	s_waitcnt lgkmcnt(0)
	s_mov_b32 s88, 0x55555555
	s_mov_b32 s89, 0xaaaaaaaa
	v_min_u32_e32 v104, v241, v0
	v_max_u32_e32 v105, v241, v0
	v_cndmask_b32_e64 v241, v105, v104, s[88:89]
	v_min_u32_e32 v106, v243, v1
	v_max_u32_e32 v107, v243, v1
	v_cndmask_b32_e64 v243, v107, v106, s[88:89]
	v_min_u32_e32 v104, v245, v2
	v_max_u32_e32 v105, v245, v2
	v_cndmask_b32_e64 v245, v105, v104, s[88:89]
	v_min_u32_e32 v106, v247, v3
	v_max_u32_e32 v107, v247, v3
	v_cndmask_b32_e64 v247, v107, v106, s[88:89]
	v_min_u32_e32 v104, v242, v4
	v_max_u32_e32 v105, v242, v4
	v_cndmask_b32_e64 v242, v105, v104, s[88:89]
	v_min_u32_e32 v106, v244, v5
	v_max_u32_e32 v107, v244, v5
	v_cndmask_b32_e64 v244, v107, v106, s[88:89]
	v_min_u32_e32 v104, v246, v6
	v_max_u32_e32 v105, v246, v6
	v_cndmask_b32_e64 v246, v105, v104, s[88:89]
	v_min_u32_e32 v106, v248, v7
	v_max_u32_e32 v107, v248, v7
	v_cndmask_b32_e64 v248, v107, v106, s[88:89]
	v_xor_b32_e32 v116, 128, v234
	ds_bpermute_b32 v0, v116, v241
	ds_bpermute_b32 v1, v116, v243
	ds_bpermute_b32 v2, v116, v245
	ds_bpermute_b32 v3, v116, v247
	ds_bpermute_b32 v4, v116, v242
	ds_bpermute_b32 v5, v116, v244
	ds_bpermute_b32 v6, v116, v246
	ds_bpermute_b32 v7, v116, v248
	s_waitcnt lgkmcnt(0)
	s_mov_b32 s88, 0xffffffff
	s_mov_b32 s89, 0x0
	v_min_u32_e32 v104, v241, v0
	v_max_u32_e32 v105, v241, v0
	v_cndmask_b32_e64 v241, v105, v104, s[88:89]
	v_min_u32_e32 v106, v243, v1
	v_max_u32_e32 v107, v243, v1
	v_cndmask_b32_e64 v243, v107, v106, s[88:89]
	v_min_u32_e32 v104, v245, v2
	v_max_u32_e32 v105, v245, v2
	v_cndmask_b32_e64 v245, v105, v104, s[88:89]
	v_min_u32_e32 v106, v247, v3
	v_max_u32_e32 v107, v247, v3
	v_cndmask_b32_e64 v247, v107, v106, s[88:89]
	s_mov_b32 s88, 0x0
	s_mov_b32 s89, 0xffffffff
	v_min_u32_e32 v104, v242, v4
	v_max_u32_e32 v105, v242, v4
	v_cndmask_b32_e64 v242, v105, v104, s[88:89]
	v_min_u32_e32 v106, v244, v5
	v_max_u32_e32 v107, v244, v5
	v_cndmask_b32_e64 v244, v107, v106, s[88:89]
	v_min_u32_e32 v104, v246, v6
	v_max_u32_e32 v105, v246, v6
	v_cndmask_b32_e64 v246, v105, v104, s[88:89]
	v_min_u32_e32 v106, v248, v7
	v_max_u32_e32 v107, v248, v7
	v_cndmask_b32_e64 v248, v107, v106, s[88:89]
	v_xor_b32_e32 v116, 64, v234
	ds_bpermute_b32 v0, v116, v241
	ds_bpermute_b32 v1, v116, v243
	ds_bpermute_b32 v2, v116, v245
	ds_bpermute_b32 v3, v116, v247
	ds_bpermute_b32 v4, v116, v242
	ds_bpermute_b32 v5, v116, v244
	ds_bpermute_b32 v6, v116, v246
	ds_bpermute_b32 v7, v116, v248
	s_waitcnt lgkmcnt(0)
	s_mov_b32 s88, 0xffff
	s_mov_b32 s89, 0xffff
	v_min_u32_e32 v104, v241, v0
	v_max_u32_e32 v105, v241, v0
	v_cndmask_b32_e64 v241, v105, v104, s[88:89]
	v_min_u32_e32 v106, v243, v1
	v_max_u32_e32 v107, v243, v1
	v_cndmask_b32_e64 v243, v107, v106, s[88:89]
	v_min_u32_e32 v104, v245, v2
	v_max_u32_e32 v105, v245, v2
	v_cndmask_b32_e64 v245, v105, v104, s[88:89]
	v_min_u32_e32 v106, v247, v3
	v_max_u32_e32 v107, v247, v3
	v_cndmask_b32_e64 v247, v107, v106, s[88:89]
	s_mov_b32 s88, 0xffff0000
	s_mov_b32 s89, 0xffff0000
	v_min_u32_e32 v104, v242, v4
	v_max_u32_e32 v105, v242, v4
	v_cndmask_b32_e64 v242, v105, v104, s[88:89]
	v_min_u32_e32 v106, v244, v5
	v_max_u32_e32 v107, v244, v5
	v_cndmask_b32_e64 v244, v107, v106, s[88:89]
	v_min_u32_e32 v104, v246, v6
	v_max_u32_e32 v105, v246, v6
	v_cndmask_b32_e64 v246, v105, v104, s[88:89]
	v_min_u32_e32 v106, v248, v7
	v_max_u32_e32 v107, v248, v7
	v_cndmask_b32_e64 v248, v107, v106, s[88:89]
	v_xor_b32_e32 v116, 32, v234
	ds_bpermute_b32 v0, v116, v241
	ds_bpermute_b32 v1, v116, v243
	ds_bpermute_b32 v2, v116, v245
	ds_bpermute_b32 v3, v116, v247
	ds_bpermute_b32 v4, v116, v242
	ds_bpermute_b32 v5, v116, v244
	ds_bpermute_b32 v6, v116, v246
	ds_bpermute_b32 v7, v116, v248
	s_waitcnt lgkmcnt(0)
	s_mov_b32 s88, 0xff00ff
	s_mov_b32 s89, 0xff00ff
	v_min_u32_e32 v104, v241, v0
	v_max_u32_e32 v105, v241, v0
	v_cndmask_b32_e64 v241, v105, v104, s[88:89]
	v_min_u32_e32 v106, v243, v1
	v_max_u32_e32 v107, v243, v1
	v_cndmask_b32_e64 v243, v107, v106, s[88:89]
	v_min_u32_e32 v104, v245, v2
	v_max_u32_e32 v105, v245, v2
	v_cndmask_b32_e64 v245, v105, v104, s[88:89]
	v_min_u32_e32 v106, v247, v3
	v_max_u32_e32 v107, v247, v3
	v_cndmask_b32_e64 v247, v107, v106, s[88:89]
	s_mov_b32 s88, 0xff00ff00
	s_mov_b32 s89, 0xff00ff00
	v_min_u32_e32 v104, v242, v4
	v_max_u32_e32 v105, v242, v4
	v_cndmask_b32_e64 v242, v105, v104, s[88:89]
	v_min_u32_e32 v106, v244, v5
	v_max_u32_e32 v107, v244, v5
	v_cndmask_b32_e64 v244, v107, v106, s[88:89]
	v_min_u32_e32 v104, v246, v6
	v_max_u32_e32 v105, v246, v6
	v_cndmask_b32_e64 v246, v105, v104, s[88:89]
	v_min_u32_e32 v106, v248, v7
	v_max_u32_e32 v107, v248, v7
	v_cndmask_b32_e64 v248, v107, v106, s[88:89]
	v_xor_b32_e32 v116, 16, v234
	ds_bpermute_b32 v0, v116, v241
	ds_bpermute_b32 v1, v116, v243
	ds_bpermute_b32 v2, v116, v245
	ds_bpermute_b32 v3, v116, v247
	ds_bpermute_b32 v4, v116, v242
	ds_bpermute_b32 v5, v116, v244
	ds_bpermute_b32 v6, v116, v246
	ds_bpermute_b32 v7, v116, v248
	s_waitcnt lgkmcnt(0)
; DEV void sort_lists(int lane, int& myi0, int& myi1, float& myg0, float& myg1) {
; #pragma unroll
;     for (int k = 2; k <= 128; k <<= 1) {
; #pragma unroll
;       for (int j = k >> 1; j >= 1; j >>= 1) {
;         if (j == 64) {
;           const bool sw_ = myi1 < myi0;
;           const int ti = sw_ ? myi1 : myi0, tj = sw_ ? myi0 : myi1; const float tg = sw_ ? myg1 : myg0, th = sw_ ? myg0 : myg1;
;           myi0 = ti; myi1 = tj; myg0 = tg; myg1 = th;
;         } else {
;           const bool lower = (lane & j) == 0;
;           {
;             const bool up = (k == 128) ? true : ((k == 64) ? true : ((lane & k) == 0));
;             const int oi = __shfl_xor(myi0, j); const float og = __shfl_xor(myg0, j);
;             const bool take = (lower == up) ? (oi < myi0) : (oi > myi0);
;             myi0 = take ? oi : myi0; myg0 = take ? og : myg0;
;           }
;           {
;             const bool up = (k == 128) ? true : ((k == 64) ? false : ((lane & k) == 0));
;             const int oi = __shfl_xor(myi1, j); const float og = __shfl_xor(myg1, j);
;             const bool take = (lower == up) ? (oi < myi1) : (oi > myi1);
;             myi1 = take ? oi : myi1; myg1 = take ? og : myg1;
;           }
;         }
;       }
;     }
; }
	s_mov_b32 s88, 0xf0f0f0f
	s_mov_b32 s89, 0xf0f0f0f
	v_min_u32_e32 v104, v241, v0
	v_max_u32_e32 v105, v241, v0
	v_cndmask_b32_e64 v241, v105, v104, s[88:89]
	v_min_u32_e32 v106, v243, v1
	v_max_u32_e32 v107, v243, v1
	v_cndmask_b32_e64 v243, v107, v106, s[88:89]
	v_min_u32_e32 v104, v245, v2
	v_max_u32_e32 v105, v245, v2
	v_cndmask_b32_e64 v245, v105, v104, s[88:89]
	v_min_u32_e32 v106, v247, v3
	v_max_u32_e32 v107, v247, v3
	v_cndmask_b32_e64 v247, v107, v106, s[88:89]
	s_mov_b32 s88, 0xf0f0f0f0
	s_mov_b32 s89, 0xf0f0f0f0
	v_min_u32_e32 v104, v242, v4
	v_max_u32_e32 v105, v242, v4
	v_cndmask_b32_e64 v242, v105, v104, s[88:89]
	v_min_u32_e32 v106, v244, v5
	v_max_u32_e32 v107, v244, v5
	v_cndmask_b32_e64 v244, v107, v106, s[88:89]
	v_min_u32_e32 v104, v246, v6
	v_max_u32_e32 v105, v246, v6
	v_cndmask_b32_e64 v246, v105, v104, s[88:89]
	v_min_u32_e32 v106, v248, v7
	v_max_u32_e32 v107, v248, v7
	v_cndmask_b32_e64 v248, v107, v106, s[88:89]
	v_xor_b32_e32 v116, 8, v234
	ds_bpermute_b32 v0, v116, v241
	ds_bpermute_b32 v1, v116, v243
	ds_bpermute_b32 v2, v116, v245
	ds_bpermute_b32 v3, v116, v247
	ds_bpermute_b32 v4, v116, v242
	ds_bpermute_b32 v5, v116, v244
	ds_bpermute_b32 v6, v116, v246
	ds_bpermute_b32 v7, v116, v248
	s_waitcnt lgkmcnt(0)
	s_mov_b32 s88, 0x33333333
	s_mov_b32 s89, 0x33333333
	v_min_u32_e32 v104, v241, v0
	v_max_u32_e32 v105, v241, v0
	v_cndmask_b32_e64 v241, v105, v104, s[88:89]
	v_min_u32_e32 v106, v243, v1
	v_max_u32_e32 v107, v243, v1
	v_cndmask_b32_e64 v243, v107, v106, s[88:89]
	v_min_u32_e32 v104, v245, v2
	v_max_u32_e32 v105, v245, v2
	v_cndmask_b32_e64 v245, v105, v104, s[88:89]
	v_min_u32_e32 v106, v247, v3
	v_max_u32_e32 v107, v247, v3
	v_cndmask_b32_e64 v247, v107, v106, s[88:89]
	s_mov_b32 s88, 0xcccccccc
	s_mov_b32 s89, 0xcccccccc
	v_min_u32_e32 v104, v242, v4
	v_max_u32_e32 v105, v242, v4
	v_cndmask_b32_e64 v242, v105, v104, s[88:89]
	v_min_u32_e32 v106, v244, v5
	v_max_u32_e32 v107, v244, v5
	v_cndmask_b32_e64 v244, v107, v106, s[88:89]
	v_min_u32_e32 v104, v246, v6
	v_max_u32_e32 v105, v246, v6
	v_cndmask_b32_e64 v246, v105, v104, s[88:89]
	v_min_u32_e32 v106, v248, v7
	v_max_u32_e32 v107, v248, v7
	v_cndmask_b32_e64 v248, v107, v106, s[88:89]
	v_xor_b32_e32 v116, 4, v234
	ds_bpermute_b32 v0, v116, v241
	ds_bpermute_b32 v1, v116, v243
	ds_bpermute_b32 v2, v116, v245
	ds_bpermute_b32 v3, v116, v247
	ds_bpermute_b32 v4, v116, v242
	ds_bpermute_b32 v5, v116, v244
	ds_bpermute_b32 v6, v116, v246
	ds_bpermute_b32 v7, v116, v248
	s_waitcnt lgkmcnt(0)
	s_mov_b32 s88, 0x55555555
	s_mov_b32 s89, 0x55555555
	v_min_u32_e32 v104, v241, v0
	v_max_u32_e32 v105, v241, v0
	v_cndmask_b32_e64 v241, v105, v104, s[88:89]
	v_min_u32_e32 v106, v243, v1
	v_max_u32_e32 v107, v243, v1
	v_cndmask_b32_e64 v243, v107, v106, s[88:89]
	v_min_u32_e32 v104, v245, v2
	v_max_u32_e32 v105, v245, v2
	v_cndmask_b32_e64 v245, v105, v104, s[88:89]
	v_min_u32_e32 v106, v247, v3
	v_max_u32_e32 v107, v247, v3
	v_cndmask_b32_e64 v247, v107, v106, s[88:89]
	s_mov_b32 s88, 0xaaaaaaaa
	s_mov_b32 s89, 0xaaaaaaaa
	v_min_u32_e32 v104, v242, v4
	v_max_u32_e32 v105, v242, v4
	v_cndmask_b32_e64 v242, v105, v104, s[88:89]
	v_min_u32_e32 v106, v244, v5
	v_max_u32_e32 v107, v244, v5
	v_cndmask_b32_e64 v244, v107, v106, s[88:89]
	v_min_u32_e32 v104, v246, v6
	v_max_u32_e32 v105, v246, v6
	v_cndmask_b32_e64 v246, v105, v104, s[88:89]
	v_min_u32_e32 v106, v248, v7
	v_max_u32_e32 v107, v248, v7
	v_cndmask_b32_e64 v248, v107, v106, s[88:89]
	v_min_u32_e32 v104, v241, v242
	v_max_u32_e32 v242, v241, v242
	v_mov_b32_e32 v241, v104
	v_min_u32_e32 v106, v243, v244
	v_max_u32_e32 v244, v243, v244
	v_mov_b32_e32 v243, v106
	v_min_u32_e32 v104, v245, v246
	v_max_u32_e32 v246, v245, v246
	v_mov_b32_e32 v245, v104
	v_min_u32_e32 v106, v247, v248
	v_max_u32_e32 v248, v247, v248
	v_mov_b32_e32 v247, v106
	v_xor_b32_e32 v116, 128, v234
	ds_bpermute_b32 v0, v116, v241
	ds_bpermute_b32 v1, v116, v243
	ds_bpermute_b32 v2, v116, v245
	ds_bpermute_b32 v3, v116, v247
	ds_bpermute_b32 v4, v116, v242
	ds_bpermute_b32 v5, v116, v244
	ds_bpermute_b32 v6, v116, v246
	ds_bpermute_b32 v7, v116, v248
	s_waitcnt lgkmcnt(0)
	s_mov_b32 s88, 0xffffffff
	s_mov_b32 s89, 0x0
	v_min_u32_e32 v104, v241, v0
	v_max_u32_e32 v105, v241, v0
	v_cndmask_b32_e64 v241, v105, v104, s[88:89]
	v_min_u32_e32 v106, v243, v1
	v_max_u32_e32 v107, v243, v1
	v_cndmask_b32_e64 v243, v107, v106, s[88:89]
	v_min_u32_e32 v104, v245, v2
	v_max_u32_e32 v105, v245, v2
	v_cndmask_b32_e64 v245, v105, v104, s[88:89]
	v_min_u32_e32 v106, v247, v3
	v_max_u32_e32 v107, v247, v3
	v_cndmask_b32_e64 v247, v107, v106, s[88:89]
	v_min_u32_e32 v104, v242, v4
	v_max_u32_e32 v105, v242, v4
	v_cndmask_b32_e64 v242, v105, v104, s[88:89]
	v_min_u32_e32 v106, v244, v5
	v_max_u32_e32 v107, v244, v5
	v_cndmask_b32_e64 v244, v107, v106, s[88:89]
	v_min_u32_e32 v104, v246, v6
	v_max_u32_e32 v105, v246, v6
	v_cndmask_b32_e64 v246, v105, v104, s[88:89]
	v_min_u32_e32 v106, v248, v7
	v_max_u32_e32 v107, v248, v7
	v_cndmask_b32_e64 v248, v107, v106, s[88:89]
	v_xor_b32_e32 v116, 64, v234
	ds_bpermute_b32 v0, v116, v241
	ds_bpermute_b32 v1, v116, v243
	ds_bpermute_b32 v2, v116, v245
	ds_bpermute_b32 v3, v116, v247
	ds_bpermute_b32 v4, v116, v242
	ds_bpermute_b32 v5, v116, v244
	ds_bpermute_b32 v6, v116, v246
	ds_bpermute_b32 v7, v116, v248
	s_waitcnt lgkmcnt(0)
; DEV void sort_lists(int lane, int& myi0, int& myi1, float& myg0, float& myg1) {
; #pragma unroll
;     for (int k = 2; k <= 128; k <<= 1) {
; #pragma unroll
;       for (int j = k >> 1; j >= 1; j >>= 1) {
;         if (j == 64) {
;           const bool sw_ = myi1 < myi0;
;           const int ti = sw_ ? myi1 : myi0, tj = sw_ ? myi0 : myi1; const float tg = sw_ ? myg1 : myg0, th = sw_ ? myg0 : myg1;
;           myi0 = ti; myi1 = tj; myg0 = tg; myg1 = th;
;         } else {
;           const bool lower = (lane & j) == 0;
;           {
;             const bool up = (k == 128) ? true : ((k == 64) ? true : ((lane & k) == 0));
;             const int oi = __shfl_xor(myi0, j); const float og = __shfl_xor(myg0, j);
;             const bool take = (lower == up) ? (oi < myi0) : (oi > myi0);
;             myi0 = take ? oi : myi0; myg0 = take ? og : myg0;
;           }
;           {
;             const bool up = (k == 128) ? true : ((k == 64) ? false : ((lane & k) == 0));
;             const int oi = __shfl_xor(myi1, j); const float og = __shfl_xor(myg1, j);
;             const bool take = (lower == up) ? (oi < myi1) : (oi > myi1);
;             myi1 = take ? oi : myi1; myg1 = take ? og : myg1;
;           }
;         }
;       }
;     }
; }
	s_mov_b32 s88, 0xffff
	s_mov_b32 s89, 0xffff
	v_min_u32_e32 v104, v241, v0
	v_max_u32_e32 v105, v241, v0
	v_cndmask_b32_e64 v241, v105, v104, s[88:89]
	v_min_u32_e32 v106, v243, v1
	v_max_u32_e32 v107, v243, v1
	v_cndmask_b32_e64 v243, v107, v106, s[88:89]
	v_min_u32_e32 v104, v245, v2
	v_max_u32_e32 v105, v245, v2
	v_cndmask_b32_e64 v245, v105, v104, s[88:89]
	v_min_u32_e32 v106, v247, v3
	v_max_u32_e32 v107, v247, v3
	v_cndmask_b32_e64 v247, v107, v106, s[88:89]
	v_min_u32_e32 v104, v242, v4
	v_max_u32_e32 v105, v242, v4
	v_cndmask_b32_e64 v242, v105, v104, s[88:89]
	v_min_u32_e32 v106, v244, v5
	v_max_u32_e32 v107, v244, v5
	v_cndmask_b32_e64 v244, v107, v106, s[88:89]
	v_min_u32_e32 v104, v246, v6
	v_max_u32_e32 v105, v246, v6
	v_cndmask_b32_e64 v246, v105, v104, s[88:89]
	v_min_u32_e32 v106, v248, v7
	v_max_u32_e32 v107, v248, v7
	v_cndmask_b32_e64 v248, v107, v106, s[88:89]
	v_xor_b32_e32 v116, 32, v234
	ds_bpermute_b32 v0, v116, v241
	ds_bpermute_b32 v1, v116, v243
	ds_bpermute_b32 v2, v116, v245
	ds_bpermute_b32 v3, v116, v247
	ds_bpermute_b32 v4, v116, v242
	ds_bpermute_b32 v5, v116, v244
	ds_bpermute_b32 v6, v116, v246
	ds_bpermute_b32 v7, v116, v248
	s_waitcnt lgkmcnt(0)
	s_mov_b32 s88, 0xff00ff
	s_mov_b32 s89, 0xff00ff
	v_min_u32_e32 v104, v241, v0
	v_max_u32_e32 v105, v241, v0
	v_cndmask_b32_e64 v241, v105, v104, s[88:89]
	v_min_u32_e32 v106, v243, v1
	v_max_u32_e32 v107, v243, v1
	v_cndmask_b32_e64 v243, v107, v106, s[88:89]
	v_min_u32_e32 v104, v245, v2
	v_max_u32_e32 v105, v245, v2
	v_cndmask_b32_e64 v245, v105, v104, s[88:89]
	v_min_u32_e32 v106, v247, v3
	v_max_u32_e32 v107, v247, v3
	v_cndmask_b32_e64 v247, v107, v106, s[88:89]
	v_min_u32_e32 v104, v242, v4
	v_max_u32_e32 v105, v242, v4
	v_cndmask_b32_e64 v242, v105, v104, s[88:89]
	v_min_u32_e32 v106, v244, v5
	v_max_u32_e32 v107, v244, v5
	v_cndmask_b32_e64 v244, v107, v106, s[88:89]
	v_min_u32_e32 v104, v246, v6
	v_max_u32_e32 v105, v246, v6
	v_cndmask_b32_e64 v246, v105, v104, s[88:89]
	v_min_u32_e32 v106, v248, v7
	v_max_u32_e32 v107, v248, v7
	v_cndmask_b32_e64 v248, v107, v106, s[88:89]
	v_xor_b32_e32 v116, 16, v234
	ds_bpermute_b32 v0, v116, v241
	ds_bpermute_b32 v1, v116, v243
	ds_bpermute_b32 v2, v116, v245
	ds_bpermute_b32 v3, v116, v247
	ds_bpermute_b32 v4, v116, v242
	ds_bpermute_b32 v5, v116, v244
	ds_bpermute_b32 v6, v116, v246
	ds_bpermute_b32 v7, v116, v248
	s_waitcnt lgkmcnt(0)
	s_mov_b32 s88, 0xf0f0f0f
	s_mov_b32 s89, 0xf0f0f0f
	v_min_u32_e32 v104, v241, v0
	v_max_u32_e32 v105, v241, v0
	v_cndmask_b32_e64 v241, v105, v104, s[88:89]
	v_min_u32_e32 v106, v243, v1
	v_max_u32_e32 v107, v243, v1
	v_cndmask_b32_e64 v243, v107, v106, s[88:89]
	v_min_u32_e32 v104, v245, v2
	v_max_u32_e32 v105, v245, v2
	v_cndmask_b32_e64 v245, v105, v104, s[88:89]
	v_min_u32_e32 v106, v247, v3
	v_max_u32_e32 v107, v247, v3
	v_cndmask_b32_e64 v247, v107, v106, s[88:89]
	v_min_u32_e32 v104, v242, v4
	v_max_u32_e32 v105, v242, v4
	v_cndmask_b32_e64 v242, v105, v104, s[88:89]
	v_min_u32_e32 v106, v244, v5
	v_max_u32_e32 v107, v244, v5
	v_cndmask_b32_e64 v244, v107, v106, s[88:89]
	v_min_u32_e32 v104, v246, v6
	v_max_u32_e32 v105, v246, v6
	v_cndmask_b32_e64 v246, v105, v104, s[88:89]
	v_min_u32_e32 v106, v248, v7
	v_max_u32_e32 v107, v248, v7
	v_cndmask_b32_e64 v248, v107, v106, s[88:89]
	v_xor_b32_e32 v116, 8, v234
	ds_bpermute_b32 v0, v116, v241
	ds_bpermute_b32 v1, v116, v243
	ds_bpermute_b32 v2, v116, v245
	ds_bpermute_b32 v3, v116, v247
	ds_bpermute_b32 v4, v116, v242
	ds_bpermute_b32 v5, v116, v244
	ds_bpermute_b32 v6, v116, v246
	ds_bpermute_b32 v7, v116, v248
	s_waitcnt lgkmcnt(0)
	s_mov_b32 s88, 0x33333333
	s_mov_b32 s89, 0x33333333
	v_min_u32_e32 v104, v241, v0
	v_max_u32_e32 v105, v241, v0
	v_cndmask_b32_e64 v241, v105, v104, s[88:89]
	v_min_u32_e32 v106, v243, v1
	v_max_u32_e32 v107, v243, v1
	v_cndmask_b32_e64 v243, v107, v106, s[88:89]
	v_min_u32_e32 v104, v245, v2
	v_max_u32_e32 v105, v245, v2
	v_cndmask_b32_e64 v245, v105, v104, s[88:89]
	v_min_u32_e32 v106, v247, v3
	v_max_u32_e32 v107, v247, v3
	v_cndmask_b32_e64 v247, v107, v106, s[88:89]
	v_min_u32_e32 v104, v242, v4
	v_max_u32_e32 v105, v242, v4
	v_cndmask_b32_e64 v242, v105, v104, s[88:89]
	v_min_u32_e32 v106, v244, v5
	v_max_u32_e32 v107, v244, v5
	v_cndmask_b32_e64 v244, v107, v106, s[88:89]
	v_min_u32_e32 v104, v246, v6
	v_max_u32_e32 v105, v246, v6
	v_cndmask_b32_e64 v246, v105, v104, s[88:89]
	v_min_u32_e32 v106, v248, v7
	v_max_u32_e32 v107, v248, v7
	v_cndmask_b32_e64 v248, v107, v106, s[88:89]
	v_xor_b32_e32 v116, 4, v234
	ds_bpermute_b32 v0, v116, v241
	ds_bpermute_b32 v1, v116, v243
	ds_bpermute_b32 v2, v116, v245
	ds_bpermute_b32 v3, v116, v247
	ds_bpermute_b32 v4, v116, v242
	ds_bpermute_b32 v5, v116, v244
	ds_bpermute_b32 v6, v116, v246
	ds_bpermute_b32 v7, v116, v248
	s_waitcnt lgkmcnt(0)
; #define PG_ISSUE(BUF, TAB, e0_) do { const int isrc_ = ((e0_) < 64) ? myi0 : myi1; \
;       _Pragma("unroll") for (int e = 0; e < 8; ++e) { const int idx_ = __builtin_amdgcn_readlane(isrc_, ((e0_) + e) & 63); \
;         BUF[e] = *(const u32x4*)((TAB) + (size_t)idx_ * 1024 + lane * 16); } } while (0)
; DEV void sort_lists(int lane, int& myi0, int& myi1, float& myg0, float& myg1) {
;     ...
;           const bool lower = (lane & j) == 0;
;           {
;             const bool up = (k == 128) ? true : ((k == 64) ? true : ((lane & k) == 0));
;             const int oi = __shfl_xor(myi0, j); const float og = __shfl_xor(myg0, j);
;             const bool take = (lower == up) ? (oi < myi0) : (oi > myi0);
;             myi0 = take ? oi : myi0; myg0 = take ? og : myg0;
;           }
;           {
;             const bool up = (k == 128) ? true : ((k == 64) ? false : ((lane & k) == 0));
;             const int oi = __shfl_xor(myi1, j); const float og = __shfl_xor(myg1, j);
;             const bool take = (lower == up) ? (oi < myi1) : (oi > myi1);
;             myi1 = take ? oi : myi1; myg1 = take ? og : myg1;
;           }
;         }
;       }
;     }
; }
; DEV void peer_gather(const Params& P, int l, int m0, const int* idxs, const float* gs) {
;     ...
;     PG_ISSUE(b0, U, 0);
; #pragma nounroll
;     for (int e0 = 0; e0 < 128; e0 += 16) {
;       PG_ISSUE(b1, U, e0 + 8);
	s_mov_b32 s88, 0x55555555
	s_mov_b32 s89, 0x55555555
	v_min_u32_e32 v104, v241, v0
	v_max_u32_e32 v105, v241, v0
	v_cndmask_b32_e64 v241, v105, v104, s[88:89]
	v_min_u32_e32 v106, v243, v1
	v_max_u32_e32 v107, v243, v1
	v_cndmask_b32_e64 v243, v107, v106, s[88:89]
	v_min_u32_e32 v104, v245, v2
	v_max_u32_e32 v105, v245, v2
	v_cndmask_b32_e64 v245, v105, v104, s[88:89]
	v_min_u32_e32 v106, v247, v3
	v_max_u32_e32 v107, v247, v3
	v_cndmask_b32_e64 v247, v107, v106, s[88:89]
	v_min_u32_e32 v104, v242, v4
	v_max_u32_e32 v105, v242, v4
	v_cndmask_b32_e64 v242, v105, v104, s[88:89]
	v_min_u32_e32 v106, v244, v5
	v_max_u32_e32 v107, v244, v5
	v_cndmask_b32_e64 v244, v107, v106, s[88:89]
	v_min_u32_e32 v104, v246, v6
	v_max_u32_e32 v105, v246, v6
	v_cndmask_b32_e64 v246, v105, v104, s[88:89]
	v_min_u32_e32 v106, v248, v7
	v_max_u32_e32 v107, v248, v7
	v_cndmask_b32_e64 v248, v107, v106, s[88:89]
	v_mov_b32_e32 v117, 0
	s_lshl_b32 s98, s2, 11
	s_add_u32 s98, s98, s101
	v_add_u32_e32 v116, s98, v234
	v_and_b32_e32 v144, 0x7f, v241
	v_and_b32_e32 v241, 0xffffff80, v241
	v_lshl_or_b32 v241, v241, 3, v144
	ds_write_b32 v116, v241 offset:0
	v_and_b32_e32 v145, 0x7f, v242
	v_and_b32_e32 v242, 0xffffff80, v242
	v_lshl_or_b32 v242, v242, 3, v145
	ds_write_b32 v116, v242 offset:256
	v_and_b32_e32 v146, 0x7f, v243
	v_and_b32_e32 v243, 0xffffff80, v243
	v_lshl_or_b32 v243, v243, 3, v146
	ds_write_b32 v116, v243 offset:512
	v_and_b32_e32 v147, 0x7f, v244
	v_and_b32_e32 v244, 0xffffff80, v244
	v_lshl_or_b32 v244, v244, 3, v147
	ds_write_b32 v116, v244 offset:768
	v_and_b32_e32 v148, 0x7f, v245
	v_and_b32_e32 v245, 0xffffff80, v245
	v_lshl_or_b32 v245, v245, 3, v148
	ds_write_b32 v116, v245 offset:1024
	v_and_b32_e32 v149, 0x7f, v246
	v_and_b32_e32 v246, 0xffffff80, v246
	v_lshl_or_b32 v246, v246, 3, v149
	ds_write_b32 v116, v246 offset:1280
	v_and_b32_e32 v150, 0x7f, v247
	v_and_b32_e32 v247, 0xffffff80, v247
	v_lshl_or_b32 v247, v247, 3, v150
	ds_write_b32 v116, v247 offset:1536
	v_and_b32_e32 v151, 0x7f, v248
	v_and_b32_e32 v248, 0xffffff80, v248
	v_lshl_or_b32 v248, v248, 3, v151
	ds_write_b32 v116, v248 offset:1792
	v_add_u32_e32 v118, 0x10000, v116
	ds_write_b32 v118, v117 offset:0
	ds_write_b32 v118, v117 offset:256
	ds_write_b32 v118, v117 offset:512
	ds_write_b32 v118, v117 offset:768
	ds_write_b32 v118, v117 offset:1024
	ds_write_b32 v118, v117 offset:1280
	ds_write_b32 v118, v117 offset:1536
	ds_write_b32 v118, v117 offset:1792
	s_add_u32 s2, s2, 1
	s_cmp_lt_u32 s2, 4
	s_cbranch_scc1 .Lpg1_p0
	s_waitcnt lgkmcnt(0)
	v_readfirstlane_b32 s80, v126
	v_readfirstlane_b32 s81, v127
	s_nop 4
	s_mov_b32 s90, 0xfffffc00
	s_mov_b32 s100, 0
	s_mov_b32 s98, 0
	s_mov_b32 s99, 0
	v_readfirstlane_b32 s82, v122
	v_readfirstlane_b32 s83, v123
	s_nop 4
	s_add_u32 vcc_lo, s3, s98
	s_lshl_b32 vcc_lo, vcc_lo, 11
	s_lshl_b32 vcc_hi, s99, 8
	s_add_u32 vcc_lo, vcc_lo, vcc_hi
	v_add_u32_e32 v119, vcc_lo, v236
	global_load_dwordx4 v[80:83], v119, s[82:83]
	global_load_dwordx4 v[84:87], v119, s[82:83] offset:16
	s_lshl_b32 vcc_lo, s98, 9
	s_add_u32 vcc_lo, vcc_lo, s101
	v_add_u32_e32 v116, vcc_lo, v234
	ds_read_b32 v134, v116
	ds_read_b32 v135, v116 offset:256
	s_lshl_b32 vcc_lo, s99, 7
	v_add_u32_e32 v240, vcc_lo, v235
	s_waitcnt lgkmcnt(0)
	ds_bpermute_b32 v142, v249, v134
	ds_bpermute_b32 v143, v250, v134
	s_waitcnt lgkmcnt(0)
	v_and_or_b32 v142, v142, s90, v240
	v_and_or_b32 v143, v143, s90, v240
	global_load_dwordx4 v[0:3], v142, s[80:81]
	global_load_dwordx4 v[4:7], v143, s[80:81]
	ds_bpermute_b32 v142, v251, v134
	ds_bpermute_b32 v143, v252, v134
	s_waitcnt lgkmcnt(0)
	v_and_or_b32 v142, v142, s90, v240
	v_and_or_b32 v143, v143, s90, v240
	global_load_dwordx4 v[8:11], v142, s[80:81]
	global_load_dwordx4 v[12:15], v143, s[80:81]
	ds_bpermute_b32 v142, v253, v134
	ds_bpermute_b32 v143, v254, v134
	s_waitcnt lgkmcnt(0)
	v_and_or_b32 v142, v142, s90, v240
	v_and_or_b32 v143, v143, s90, v240
	global_load_dwordx4 v[16:19], v142, s[80:81]
	global_load_dwordx4 v[20:23], v143, s[80:81]
	ds_bpermute_b32 v142, v255, v134
	ds_bpermute_b32 v143, v153, v134
	s_waitcnt lgkmcnt(0)
	v_and_or_b32 v142, v142, s90, v240
	v_and_or_b32 v143, v143, s90, v240
	global_load_dwordx4 v[24:27], v142, s[80:81]
	global_load_dwordx4 v[28:31], v143, s[80:81]
	ds_bpermute_b32 v142, v249, v135
	ds_bpermute_b32 v143, v250, v135
	s_waitcnt lgkmcnt(0)
	v_and_or_b32 v142, v142, s90, v240
	v_and_or_b32 v143, v143, s90, v240
	global_load_dwordx4 v[32:35], v142, s[80:81]
	global_load_dwordx4 v[36:39], v143, s[80:81]
	ds_bpermute_b32 v142, v251, v135
	ds_bpermute_b32 v143, v252, v135
	s_waitcnt lgkmcnt(0)
	v_and_or_b32 v142, v142, s90, v240
	v_and_or_b32 v143, v143, s90, v240
	global_load_dwordx4 v[40:43], v142, s[80:81]
	global_load_dwordx4 v[44:47], v143, s[80:81]
	ds_bpermute_b32 v142, v253, v135
	ds_bpermute_b32 v143, v254, v135
	s_waitcnt lgkmcnt(0)
	v_and_or_b32 v142, v142, s90, v240
	v_and_or_b32 v143, v143, s90, v240
	global_load_dwordx4 v[48:51], v142, s[80:81]
	global_load_dwordx4 v[52:55], v143, s[80:81]
	ds_bpermute_b32 v142, v255, v135
	ds_bpermute_b32 v143, v153, v135
	s_waitcnt lgkmcnt(0)
	v_and_or_b32 v142, v142, s90, v240
	v_and_or_b32 v143, v143, s90, v240
	global_load_dwordx4 v[56:59], v142, s[80:81]
	global_load_dwordx4 v[60:63], v143, s[80:81]
	s_mov_b32 s92, 1
	s_lshl_b32 vcc_lo, s92, 9
	s_add_u32 vcc_lo, vcc_lo, s101
	v_add_u32_e32 v116, vcc_lo, v234
	ds_read_b32 v134, v116
	ds_read_b32 v135, v116 offset:256

.Lpg1_act:
	v_readlane_b32 s82, v232, 1
	v_readlane_b32 s83, v232, 2
	s_nop 4
	s_lshl_b32 s98, s2, 11
	s_add_u32 s98, s98, s101
	v_add_u32_e32 v116, s98, v234
	v_add_u32_e32 v117, 0x10000, v116
	ds_read_b32 v0, v116 offset:0
	ds_read_b32 v8, v117 offset:0
	ds_read_b32 v1, v116 offset:256
	ds_read_b32 v9, v117 offset:256
	ds_read_b32 v2, v116 offset:512
	ds_read_b32 v10, v117 offset:512
	ds_read_b32 v3, v116 offset:768
	ds_read_b32 v11, v117 offset:768
	ds_read_b32 v4, v116 offset:1024
	ds_read_b32 v12, v117 offset:1024
	ds_read_b32 v5, v116 offset:1280
	ds_read_b32 v13, v117 offset:1280
	ds_read_b32 v6, v116 offset:1536
	ds_read_b32 v14, v117 offset:1536
	ds_read_b32 v7, v116 offset:1792
	ds_read_b32 v15, v117 offset:1792
	s_waitcnt lgkmcnt(0)
	s_lshl_b32 s99, s2, 2
	s_add_u32 s99, s99, s33
	s_add_u32 s99, s99, 0
	s_lshl_b32 s99, s99, 9
	v_and_b32_e32 v0, 0x7f, v0
	v_lshl_add_u32 v0, v0, 2, s99
	global_load_dword v16, v0, s[82:83]
	v_and_b32_e32 v1, 0x7f, v1
	v_lshl_add_u32 v1, v1, 2, s99
	global_load_dword v17, v1, s[82:83]
	s_lshl_b32 s99, s2, 2
	s_add_u32 s99, s99, s33
	s_add_u32 s99, s99, 1
	s_lshl_b32 s99, s99, 9
	v_and_b32_e32 v2, 0x7f, v2
	v_lshl_add_u32 v2, v2, 2, s99
	global_load_dword v18, v2, s[82:83]
	v_and_b32_e32 v3, 0x7f, v3
	v_lshl_add_u32 v3, v3, 2, s99
	global_load_dword v19, v3, s[82:83]
	s_lshl_b32 s99, s2, 2
	s_add_u32 s99, s99, s33
	s_add_u32 s99, s99, 2
	s_lshl_b32 s99, s99, 9
	v_and_b32_e32 v4, 0x7f, v4
	v_lshl_add_u32 v4, v4, 2, s99
	global_load_dword v20, v4, s[82:83]
	v_and_b32_e32 v5, 0x7f, v5
	v_lshl_add_u32 v5, v5, 2, s99
	global_load_dword v21, v5, s[82:83]
	s_lshl_b32 s99, s2, 2
	s_add_u32 s99, s99, s33
	s_add_u32 s99, s99, 3
	s_lshl_b32 s99, s99, 9
	v_and_b32_e32 v6, 0x7f, v6
	v_lshl_add_u32 v6, v6, 2, s99
	global_load_dword v22, v6, s[82:83]
	v_and_b32_e32 v7, 0x7f, v7
	v_lshl_add_u32 v7, v7, 2, s99
	global_load_dword v23, v7, s[82:83]
	v_mul_f32_e32 v8, 0x3c800000, v8
	v_mul_f32_e32 v9, 0x3c800000, v9
	v_mul_f32_e32 v10, 0x3c800000, v10
	v_mul_f32_e32 v11, 0x3c800000, v11
	v_mul_f32_e32 v12, 0x3c800000, v12
	v_mul_f32_e32 v13, 0x3c800000, v13
	v_mul_f32_e32 v14, 0x3c800000, v14
	v_mul_f32_e32 v15, 0x3c800000, v15
	v_mul_f32_e32 v24, 0x3d372713, v8
	v_mul_f32_e32 v25, 0x3d372713, v9
	v_mul_f32_e32 v26, 0x3d372713, v10
	v_mul_f32_e32 v27, 0x3d372713, v11
	v_mul_f32_e32 v28, 0x3d372713, v12
	v_mul_f32_e32 v29, 0x3d372713, v13
	v_mul_f32_e32 v30, 0x3d372713, v14
	v_mul_f32_e32 v31, 0x3d372713, v15
	v_mul_f32_e32 v24, v8, v24
	v_mul_f32_e32 v25, v9, v25
	v_mul_f32_e32 v26, v10, v26
	v_mul_f32_e32 v27, v11, v27
	v_mul_f32_e32 v28, v12, v28
	v_mul_f32_e32 v29, v13, v29
	v_mul_f32_e32 v30, v14, v30
	v_mul_f32_e32 v31, v15, v31
	v_fma_f32 v24, v8, v24, v8
	v_fma_f32 v25, v9, v25, v9
	v_fma_f32 v26, v10, v26, v10
	v_fma_f32 v27, v11, v27, v11
	v_fma_f32 v28, v12, v28, v12
	v_fma_f32 v29, v13, v29, v13
	v_fma_f32 v30, v14, v30, v14
	v_fma_f32 v31, v15, v31, v15
	v_mul_f32_e32 v24, 0xbfcc422a, v24
	v_mul_f32_e32 v25, 0xbfcc422a, v25
	v_mul_f32_e32 v26, 0xbfcc422a, v26
	v_mul_f32_e32 v27, 0xbfcc422a, v27
	v_mul_f32_e32 v28, 0xbfcc422a, v28
	v_mul_f32_e32 v29, 0xbfcc422a, v29
	v_mul_f32_e32 v30, 0xbfcc422a, v30
	v_mul_f32_e32 v31, 0xbfcc422a, v31
	v_mul_f32_e32 v24, 0x3fb8aa3b, v24
	v_mul_f32_e32 v25, 0x3fb8aa3b, v25
	v_mul_f32_e32 v26, 0x3fb8aa3b, v26
	v_mul_f32_e32 v27, 0x3fb8aa3b, v27
	v_mul_f32_e32 v28, 0x3fb8aa3b, v28
	v_mul_f32_e32 v29, 0x3fb8aa3b, v29
	v_mul_f32_e32 v30, 0x3fb8aa3b, v30
	v_mul_f32_e32 v31, 0x3fb8aa3b, v31
	v_exp_f32_e32 v24, v24
	v_exp_f32_e32 v25, v25
	v_exp_f32_e32 v26, v26
	v_exp_f32_e32 v27, v27
	v_exp_f32_e32 v28, v28
	v_exp_f32_e32 v29, v29
	v_exp_f32_e32 v30, v30
	v_exp_f32_e32 v31, v31
	s_nop 0
	v_add_f32_e32 v24, 1.0, v24
	v_add_f32_e32 v25, 1.0, v25
	v_add_f32_e32 v26, 1.0, v26
	v_add_f32_e32 v27, 1.0, v27
	v_add_f32_e32 v28, 1.0, v28
	v_add_f32_e32 v29, 1.0, v29
	v_add_f32_e32 v30, 1.0, v30
	v_add_f32_e32 v31, 1.0, v31
	v_rcp_f32_e32 v24, v24
	v_rcp_f32_e32 v25, v25
	v_rcp_f32_e32 v26, v26
	v_rcp_f32_e32 v27, v27
	v_rcp_f32_e32 v28, v28
	v_rcp_f32_e32 v29, v29
	v_rcp_f32_e32 v30, v30
	v_rcp_f32_e32 v31, v31
	s_nop 0
	v_mul_f32_e32 v24, v8, v24
	v_mul_f32_e32 v25, v9, v25
	v_mul_f32_e32 v26, v10, v26
	v_mul_f32_e32 v27, v11, v27
	v_mul_f32_e32 v28, v12, v28
	v_mul_f32_e32 v29, v13, v29
	v_mul_f32_e32 v30, v14, v30
	v_mul_f32_e32 v31, v15, v31
	s_waitcnt vmcnt(0)
	v_mul_f32_e32 v24, v24, v16
	ds_write_b32 v117, v24 offset:0
	v_mul_f32_e32 v25, v25, v17
	ds_write_b32 v117, v25 offset:256
	v_mul_f32_e32 v26, v26, v18
	ds_write_b32 v117, v26 offset:512
	v_mul_f32_e32 v27, v27, v19
	ds_write_b32 v117, v27 offset:768
	v_mul_f32_e32 v28, v28, v20
	ds_write_b32 v117, v28 offset:1024
	v_mul_f32_e32 v29, v29, v21
	ds_write_b32 v117, v29 offset:1280
	v_mul_f32_e32 v30, v30, v22
	ds_write_b32 v117, v30 offset:1536
	v_mul_f32_e32 v31, v31, v23
	ds_write_b32 v117, v31 offset:1792
	s_add_u32 s2, s2, 1
	s_cmp_lt_u32 s2, 4
	s_cbranch_scc1 .Lpg1_act
; #define PG_ISSUE(BUF, TAB, e0_) do { const int isrc_ = ((e0_) < 64) ? myi0 : myi1; \
;       _Pragma("unroll") for (int e = 0; e < 8; ++e) { const int idx_ = __builtin_amdgcn_readlane(isrc_, ((e0_) + e) & 63); \
;         BUF[e] = *(const u32x4*)((TAB) + (size_t)idx_ * 1024 + lane * 16); } } while (0)
; DEV void peer_gather(const Params& P, int l, int m0, const int* idxs, const float* gs) {
;     ...
; #pragma nounroll
;     for (int e0 = 0; e0 < 128; e0 += 16) {
;       PG_ISSUE(b1, V, e0 + 8);
;       if (e0 == 64 && i + 1 < 16) sort_lists(lane, ni0, ni1, ng0, ng1);
;       PG_V16(b0, e0);
;       if (e0 + 16 < 128) PG_ISSUE(b0, V, e0 + 16);
;       PG_V16(b1, e0 + 8);
	s_waitcnt lgkmcnt(0)
	v_readfirstlane_b32 s80, v128
	v_readfirstlane_b32 s81, v129
	s_nop 4
	s_mov_b32 s90, 0xfffffc00
	s_mov_b32 s100, 0
	s_mov_b32 s98, 0
	s_mov_b32 s99, 0
	s_lshl_b32 vcc_lo, s98, 9
	s_add_u32 vcc_lo, vcc_lo, s101
	v_add_u32_e32 v116, vcc_lo, v234
	ds_read_b32 v134, v116
	ds_read_b32 v135, v116 offset:256
	s_lshl_b32 vcc_lo, s99, 7
	v_add_u32_e32 v240, vcc_lo, v235
	s_waitcnt lgkmcnt(0)
	ds_bpermute_b32 v142, v249, v134
	ds_bpermute_b32 v143, v250, v134
	s_waitcnt lgkmcnt(0)
	v_and_or_b32 v142, v142, s90, v240
	v_and_or_b32 v143, v143, s90, v240
	global_load_dwordx4 v[0:3], v142, s[80:81]
	global_load_dwordx4 v[4:7], v143, s[80:81]
	ds_bpermute_b32 v142, v251, v134
	ds_bpermute_b32 v143, v252, v134
	s_waitcnt lgkmcnt(0)
	v_and_or_b32 v142, v142, s90, v240
	v_and_or_b32 v143, v143, s90, v240
	global_load_dwordx4 v[8:11], v142, s[80:81]
	global_load_dwordx4 v[12:15], v143, s[80:81]
	ds_bpermute_b32 v142, v253, v134
	ds_bpermute_b32 v143, v254, v134
	s_waitcnt lgkmcnt(0)
	v_and_or_b32 v142, v142, s90, v240
	v_and_or_b32 v143, v143, s90, v240
	global_load_dwordx4 v[16:19], v142, s[80:81]
	global_load_dwordx4 v[20:23], v143, s[80:81]
	ds_bpermute_b32 v142, v255, v134
	ds_bpermute_b32 v143, v153, v134
	s_waitcnt lgkmcnt(0)
	v_and_or_b32 v142, v142, s90, v240
	v_and_or_b32 v143, v143, s90, v240
	global_load_dwordx4 v[24:27], v142, s[80:81]
	global_load_dwordx4 v[28:31], v143, s[80:81]
	ds_bpermute_b32 v142, v249, v135
	ds_bpermute_b32 v143, v250, v135
	s_waitcnt lgkmcnt(0)
	v_and_or_b32 v142, v142, s90, v240
	v_and_or_b32 v143, v143, s90, v240
	global_load_dwordx4 v[32:35], v142, s[80:81]
	global_load_dwordx4 v[36:39], v143, s[80:81]
	ds_bpermute_b32 v142, v251, v135
	ds_bpermute_b32 v143, v252, v135
	s_waitcnt lgkmcnt(0)
	v_and_or_b32 v142, v142, s90, v240
	v_and_or_b32 v143, v143, s90, v240
	global_load_dwordx4 v[40:43], v142, s[80:81]
	global_load_dwordx4 v[44:47], v143, s[80:81]
	ds_bpermute_b32 v142, v253, v135
	ds_bpermute_b32 v143, v254, v135
	s_waitcnt lgkmcnt(0)
	v_and_or_b32 v142, v142, s90, v240
	v_and_or_b32 v143, v143, s90, v240
	global_load_dwordx4 v[48:51], v142, s[80:81]
	global_load_dwordx4 v[52:55], v143, s[80:81]
	ds_bpermute_b32 v142, v255, v135
	ds_bpermute_b32 v143, v153, v135
	s_waitcnt lgkmcnt(0)
	v_and_or_b32 v142, v142, s90, v240
	v_and_or_b32 v143, v143, s90, v240
	global_load_dwordx4 v[56:59], v142, s[80:81]
	global_load_dwordx4 v[60:63], v143, s[80:81]
	s_mov_b32 s92, 1
	s_lshl_b32 vcc_lo, s92, 9
	s_add_u32 vcc_lo, vcc_lo, s101
	v_add_u32_e32 v116, vcc_lo, v234
	ds_read_b32 v134, v116
	ds_read_b32 v135, v116 offset:256
	s_lshl_b32 vcc_lo, s98, 9
	s_add_u32 vcc_lo, vcc_lo, s101
	s_add_u32 vcc_lo, vcc_lo, 0x10000
	v_add_u32_e32 v117, vcc_lo, v234
	ds_read_b32 v136, v117
	ds_read_b32 v137, v117 offset:256
	s_waitcnt vmcnt(0)
